# v23 + L2 touch of the unit's K and V^T lines at attention-unit start (LDS-DMA dummy loads)
# speedup vs baseline: 1.0019x; 1.0010x over previous
; __device__ __forceinline__ void attn_wg_unit(const Args& args, int l, int u, LAS unsigned char* lds, int tid_in) {
;     ...
;     const int lane = tid & 63, wave = __builtin_amdgcn_readfirstlane(tid >> 6), r32 = lane & 31, hh = lane >> 5;
;     const int panel = u >> 2, head = u & 3, b = panel >> 5, row0 = panel * 256 + 32 * wave;
;     const bf16_t* Kb = (const bf16_t*)(ws + WS_KP) + (size_t)(l * NBATCH + b) * MEMLEN * MW + head * MHD;
;     const bf16_t* Vt = (const bf16_t*)(ws + WS_VTP) + (size_t)((l * NBATCH + b) * MHEADS + head) * MHD * MEMLEN;
;     LAS unsigned char* buf = lds + ATT_LDS;
;     const int kkey = tid & 15, kdch = tid >> 4;
;     const bf16_t* ksrc = Kb + (size_t)kkey * MW + 8 * kdch;
;     const int kdst = (kdch >> 1) * 1024 + (kkey + 32 * (kdch & 1)) * 16;
;     const int vd = tid >> 1, vs = tid & 1;
;     const bf16_t* vsrc = Vt + (size_t)vd * MEMLEN + 16 * vs;
;     const int vdst = ((vd >> 5) * 2 + vs) * 1024 + (vd & 31) * 16;
;     bf16x8 qf[16];
;     { const bf16_t* qp = PROJ + (size_t)(row0 + r32) * INC + C_Q + head * MHD + 8 * hh;
; #pragma unroll
;       for (int ks = 0; ks < 16; ++ks) qf[ks] = *(const bf16x8*)(qp + 16 * ks); }
;     u32x4 s0, s1;
;     s0 = *(const u32x4*)(ksrc); s1 = *(const u32x4*)(ksrc + (size_t)16 * MW);
;     *(LAS u32x4*)(buf + kdst) = s0; *(LAS u32x4*)(buf + kdst + 256) = s1;
;     __syncthreads();
;     f32x16 st[8];
; #pragma unroll
;     for (int kt = 0; kt < 8; ++kt) {
;         if (kt < 7) { s0 = *(const u32x4*)(ksrc + (size_t)(32 * (kt + 1)) * MW); s1 = *(const u32x4*)(ksrc + (size_t)(32 * (kt + 1) + 16) * MW); }
;         else { s0 = *(const u32x4*)(vsrc); s1 = *(const u32x4*)(vsrc + 8); }
;         const LAS unsigned char* cb = buf + (kt & 1) * 16384 + lane * 16;
;         f32x16 acc;
; #pragma unroll
;         for (int i = 0; i < 16; ++i) acc[i] = 0.f;
; #pragma unroll
;         for (int ks = 0; ks < 16; ++ks) { const bf16x8 kf = *(const LAS bf16x8*)(cb + ks * 1024); acc = __builtin_amdgcn_mfma_f32_32x32x16_bf16(kf, qf[ks], acc, 0, 0, 0); }
;         st[kt] = acc;
;         LAS unsigned char* nb = buf + ((kt + 1) & 1) * 16384;
;         if (kt < 7) { *(LAS u32x4*)(nb + kdst) = s0; *(LAS u32x4*)(nb + kdst + 256) = s1; }
;         else { *(LAS u32x4*)(nb + vdst) = (u32x4){s0.x, s0.y, s1.x, s1.y}; *(LAS u32x4*)(nb + vdst + 512) = (u32x4){s0.z, s0.w, s1.z, s1.w}; }
;         __syncthreads();
;     }
.LBB0_646:
	s_waitcnt vmcnt(0)
	v_mov_b32_e32 v7, v0
	s_ashr_i32 s1, s8, 7
	v_readfirstlane_b32 s0, v7
	s_ashr_i32 s0, s0, 1
	s_and_b32 s2, s7, 0xffffff00
	s_andn2_b32 s0, s0, 31
	s_add_i32 s9, s0, s2
	s_add_i32 s2, s1, s6
	s_ashr_i32 s3, s2, 31
	s_and_b32 s4, s8, 3
	s_lshl_b64 s[0:1], s[2:3], 19
	s_add_u32 s0, s84, s0
	s_addc_u32 s1, s38, s1
	s_lshl_b32 s80, s4, 9
	s_add_u32 s0, s0, s80
	s_addc_u32 s1, s1, 0
	s_lshl_b32 s2, s2, 2
	s_or_b32 s2, s2, s4
	v_ashrrev_i32_e32 v2, 4, v7
	v_ashrrev_i32_e32 v8, 1, v7
	s_ashr_i32 s3, s2, 31
	s_waitcnt vmcnt(0)
	v_and_b32_e32 v12, 15, v7
	v_lshlrev_b32_e32 v4, 3, v2
	v_lshlrev_b32_e32 v2, 5, v2
	v_ashrrev_i32_e32 v9, 31, v8
	s_lshl_b64 s[4:5], s[2:3], 17
	v_and_or_b32 v14, v2, 32, v12
	v_and_b32_e32 v15, 1, v7
	s_waitcnt lgkmcnt(0)
	v_lshlrev_b64 v[2:3], 9, v[8:9]
	v_lshrrev_b32_e32 v9, 5, v7
	s_mov_b32 s2, 0x3ffffe
	v_lshlrev_b32_e32 v8, 4, v8
	v_and_or_b32 v16, v9, s2, v15
	v_and_b32_e32 v192, 0x1f0, v8
	v_and_or_b32 v212, v7, 31, s9
	v_mov_b64_e32 v[8:9], s[66:67]
	v_bfe_u32 v10, v7, 5, 1
	v_mad_i64_i32 v[8:9], s[2:3], v212, s48, v[8:9]
	v_lshl_add_u64 v[8:9], v[8:9], 0, s[80:81]
	v_lshlrev_b32_e32 v130, 3, v10
	v_lshlrev_b32_e32 v10, 4, v10
	v_mov_b32_e32 v11, v131
	v_lshl_add_u64 v[8:9], v[8:9], 0, v[10:11]
	v_lshl_add_u64 v[10:11], v[8:9], 0, s[26:27]
	v_add_co_u32_e32 v8, vcc, s16, v8
	v_ashrrev_i32_e32 v5, 31, v4
	s_nop 0
	v_addc_co_u32_e32 v9, vcc, 0, v9, vcc
	global_load_dwordx4 v[114:117], v[8:9], off offset:2048
	global_load_dwordx4 v[188:191], v[10:11], off offset:32
	global_load_dwordx4 v[184:187], v[10:11], off offset:64
	global_load_dwordx4 v[180:183], v[10:11], off offset:96
	global_load_dwordx4 v[176:179], v[10:11], off offset:128
	global_load_dwordx4 v[172:175], v[10:11], off offset:160
	global_load_dwordx4 v[168:171], v[10:11], off offset:192
	global_load_dwordx4 v[164:167], v[10:11], off offset:224
	global_load_dwordx4 v[160:163], v[10:11], off offset:256
	global_load_dwordx4 v[156:159], v[10:11], off offset:288
	global_load_dwordx4 v[152:155], v[10:11], off offset:320
	global_load_dwordx4 v[148:151], v[10:11], off offset:352
	global_load_dwordx4 v[144:147], v[10:11], off offset:384
	global_load_dwordx4 v[140:143], v[10:11], off offset:416
	global_load_dwordx4 v[136:139], v[10:11], off offset:448
	global_load_dwordx4 v[132:135], v[10:11], off offset:480
	v_lshlrev_b32_e32 v8, 11, v12
	v_mov_b32_e32 v9, v131
	v_lshlrev_b32_e32 v13, 5, v7
	s_add_u32 s4, s29, s4
	v_lshl_add_u64 v[8:9], s[0:1], 0, v[8:9]
	s_addc_u32 s5, s49, s5
	s_mov_b32 m0, 0x22000
	v_lshrrev_b32_e32 v196, 2, v7
	v_lshlrev_b32_e32 v196, 11, v196
	v_and_b32_e32 v197, 3, v7
	v_lshl_add_u32 v196, v197, 7, v196
	v_lshlrev_b32_e32 v197, 7, v7
	global_load_lds_dword v196, s[0:1]
	global_load_lds_dword v197, s[4:5]
	v_add_u32_e32 v196, 0x40000, v196
	v_add_u32_e32 v197, 0x10000, v197
	global_load_lds_dword v196, s[0:1]
	global_load_lds_dword v197, s[4:5]
	v_lshl_add_u64 v[118:119], v[4:5], 1, v[8:9]
	v_and_b32_e32 v4, 0xfffffc00, v13
	v_and_b32_e32 v6, 63, v7
	v_lshl_or_b32 v7, v14, 4, v4
	v_lshl_add_u64 v[2:3], s[4:5], 0, v[2:3]
	v_lshlrev_b32_e32 v4, 5, v15
	v_mov_b32_e32 v5, v131
	v_add_co_u32_e32 v8, vcc, s14, v118
	v_lshl_add_u64 v[214:215], v[2:3], 0, v[4:5]
	global_load_dwordx4 v[2:5], v[118:119], off
	v_addc_co_u32_e32 v9, vcc, 0, v119, vcc
	global_load_dwordx4 v[8:11], v[8:9], off
	v_add_u32_e32 v120, 0, v7
	v_lshl_add_u32 v211, v6, 4, 0
	v_lshlrev_b32_e32 v193, 10, v16
	s_mov_b32 s0, 0x18000
	v_add3_u32 v216, 0, v193, v192
	v_ashrrev_i32_e32 v213, 31, v212
	s_add_i32 s8, s8, s85
	s_add_i32 s7, s7, s96
	s_cmpk_gt_i32 s8, 0xff
	s_waitcnt vmcnt(1)
	ds_write_b128 v120, v[2:5] offset:8192
	s_waitcnt vmcnt(0)
	ds_write_b128 v120, v[8:11] offset:8448
	s_waitcnt lgkmcnt(0)
	s_barrier
	v_add_co_u32_e32 v200, vcc, s0, v118
	s_mov_b32 s0, 0x28000
	s_nop 0
	v_addc_co_u32_e32 v201, vcc, 0, v119, vcc
	v_add_co_u32_e32 v196, vcc, s24, v118
	global_load_dwordx4 v[200:203], v[200:201], off
	s_nop 0
	v_addc_co_u32_e32 v197, vcc, 0, v119, vcc
	global_load_dwordx4 v[196:199], v[196:197], off
	ds_read_b128 v[18:21], v211 offset:8192
	ds_read_b128 v[26:29], v211 offset:9216
	ds_read_b128 v[30:33], v211 offset:10240
	ds_read_b128 v[34:37], v211 offset:11264
	ds_read_b128 v[38:41], v211 offset:12288
	ds_read_b128 v[42:45], v211 offset:13312
	s_waitcnt lgkmcnt(5)
	v_mfma_f32_32x32x16_bf16 v[2:17], v[18:21], v[114:117], 0
	ds_read_b128 v[46:49], v211 offset:14336
	s_waitcnt lgkmcnt(5)
	v_mfma_f32_32x32x16_bf16 v[2:17], v[26:29], v[188:191], v[2:17]
	ds_read_b128 v[50:53], v211 offset:15360
	s_waitcnt lgkmcnt(5)
	v_mfma_f32_32x32x16_bf16 v[2:17], v[30:33], v[184:187], v[2:17]
	ds_read_b128 v[18:21], v211 offset:16384
	s_waitcnt lgkmcnt(5)
	v_mfma_f32_32x32x16_bf16 v[2:17], v[34:37], v[180:183], v[2:17]
	ds_read_b128 v[26:29], v211 offset:17408
	s_waitcnt lgkmcnt(5)
	v_mfma_f32_32x32x16_bf16 v[2:17], v[38:41], v[176:179], v[2:17]
	ds_read_b128 v[30:33], v211 offset:18432
	s_waitcnt lgkmcnt(5)
	v_mfma_f32_32x32x16_bf16 v[2:17], v[42:45], v[172:175], v[2:17]
	ds_read_b128 v[34:37], v211 offset:19456
	s_waitcnt lgkmcnt(5)
	v_mfma_f32_32x32x16_bf16 v[2:17], v[46:49], v[168:171], v[2:17]
	ds_read_b128 v[38:41], v211 offset:20480
	s_waitcnt lgkmcnt(5)
	v_mfma_f32_32x32x16_bf16 v[2:17], v[50:53], v[164:167], v[2:17]
	ds_read_b128 v[42:45], v211 offset:21504
	s_waitcnt lgkmcnt(5)
	v_mfma_f32_32x32x16_bf16 v[2:17], v[18:21], v[160:163], v[2:17]
	ds_read_b128 v[46:49], v211 offset:22528
	s_waitcnt lgkmcnt(5)
	v_mfma_f32_32x32x16_bf16 v[2:17], v[26:29], v[156:159], v[2:17]
	ds_read_b128 v[50:53], v211 offset:23552
	s_waitcnt lgkmcnt(5)
	v_mfma_f32_32x32x16_bf16 v[2:17], v[30:33], v[152:155], v[2:17]
	s_waitcnt lgkmcnt(4)
	v_mfma_f32_32x32x16_bf16 v[2:17], v[34:37], v[148:151], v[2:17]
	s_waitcnt lgkmcnt(3)
	v_mfma_f32_32x32x16_bf16 v[2:17], v[38:41], v[144:147], v[2:17]
	s_waitcnt lgkmcnt(2)
	v_mfma_f32_32x32x16_bf16 v[2:17], v[42:45], v[140:143], v[2:17]
	s_waitcnt lgkmcnt(1)
	v_mfma_f32_32x32x16_bf16 v[2:17], v[46:49], v[136:139], v[2:17]
	s_waitcnt lgkmcnt(0)
	v_mfma_f32_32x32x16_bf16 v[2:17], v[50:53], v[132:135], v[2:17]
	s_waitcnt vmcnt(0)
	ds_write_b128 v120, v[196:199] offset:24576
	ds_write_b128 v120, v[200:203] offset:24832
	s_waitcnt lgkmcnt(0)
	s_barrier
; #define LAS __attribute__((address_space(3)))
; __device__ __forceinline__ void attn_wg_unit(const Args& args, int l, int u, LAS unsigned char* lds, int tid_in) {
;     ...
; #pragma unroll
;     for (int kt = 0; kt < 8; ++kt) {
;         if (kt < 7) { s0 = *(const u32x4*)(ksrc + (size_t)(32 * (kt + 1)) * MW); s1 = *(const u32x4*)(ksrc + (size_t)(32 * (kt + 1) + 16) * MW); }
;         else { s0 = *(const u32x4*)(vsrc); s1 = *(const u32x4*)(vsrc + 8); }
;         const LAS unsigned char* cb = buf + (kt & 1) * 16384 + lane * 16;
;         f32x16 acc;
; #pragma unroll
;         for (int i = 0; i < 16; ++i) acc[i] = 0.f;
; #pragma unroll
;         for (int ks = 0; ks < 16; ++ks) { const bf16x8 kf = *(const LAS bf16x8*)(cb + ks * 1024); acc = __builtin_amdgcn_mfma_f32_32x32x16_bf16(kf, qf[ks], acc, 0, 0, 0); }
;         st[kt] = acc;
;         LAS unsigned char* nb = buf + ((kt + 1) & 1) * 16384;
;         if (kt < 7) { *(LAS u32x4*)(nb + kdst) = s0; *(LAS u32x4*)(nb + kdst + 256) = s1; }
;         else { *(LAS u32x4*)(nb + vdst) = (u32x4){s0.x, s0.y, s1.x, s1.y}; *(LAS u32x4*)(nb + vdst + 512) = (u32x4){s0.z, s0.w, s1.z, s1.w}; }
;         __syncthreads();
;     }
	v_add_co_u32_e32 v200, vcc, s0, v118
	s_mov_b32 s0, 0x38000
	s_nop 0
	v_addc_co_u32_e32 v201, vcc, 0, v119, vcc
	v_add_co_u32_e32 v196, vcc, s17, v118
	global_load_dwordx4 v[200:203], v[200:201], off
	s_nop 0
	v_addc_co_u32_e32 v197, vcc, 0, v119, vcc
	global_load_dwordx4 v[196:199], v[196:197], off
	ds_read_b128 v[34:37], v211 offset:24576
	ds_read_b128 v[42:45], v211 offset:25600
	ds_read_b128 v[46:49], v211 offset:26624
	ds_read_b128 v[50:53], v211 offset:27648
	ds_read_b128 v[54:57], v211 offset:28672
	ds_read_b128 v[58:61], v211 offset:29696
	s_waitcnt lgkmcnt(5)
	v_mfma_f32_32x32x16_bf16 v[18:33], v[34:37], v[114:117], 0
	ds_read_b128 v[62:65], v211 offset:30720
	s_waitcnt lgkmcnt(5)
	v_mfma_f32_32x32x16_bf16 v[18:33], v[42:45], v[188:191], v[18:33]
	ds_read_b128 v[66:69], v211 offset:31744
	s_waitcnt lgkmcnt(5)
	v_mfma_f32_32x32x16_bf16 v[18:33], v[46:49], v[184:187], v[18:33]
	ds_read_b128 v[34:37], v211 offset:32768
	s_waitcnt lgkmcnt(5)
	v_mfma_f32_32x32x16_bf16 v[18:33], v[50:53], v[180:183], v[18:33]
	ds_read_b128 v[42:45], v211 offset:33792
	s_waitcnt lgkmcnt(5)
	v_mfma_f32_32x32x16_bf16 v[18:33], v[54:57], v[176:179], v[18:33]
	ds_read_b128 v[46:49], v211 offset:34816
	s_waitcnt lgkmcnt(5)
	v_mfma_f32_32x32x16_bf16 v[18:33], v[58:61], v[172:175], v[18:33]
	ds_read_b128 v[50:53], v211 offset:35840
	s_waitcnt lgkmcnt(5)
	v_mfma_f32_32x32x16_bf16 v[18:33], v[62:65], v[168:171], v[18:33]
	ds_read_b128 v[54:57], v211 offset:36864
	s_waitcnt lgkmcnt(5)
	v_mfma_f32_32x32x16_bf16 v[18:33], v[66:69], v[164:167], v[18:33]
	ds_read_b128 v[58:61], v211 offset:37888
	s_waitcnt lgkmcnt(5)
	v_mfma_f32_32x32x16_bf16 v[18:33], v[34:37], v[160:163], v[18:33]
	ds_read_b128 v[62:65], v211 offset:38912
	s_waitcnt lgkmcnt(5)
	v_mfma_f32_32x32x16_bf16 v[18:33], v[42:45], v[156:159], v[18:33]
	ds_read_b128 v[66:69], v211 offset:39936
	s_waitcnt lgkmcnt(5)
	v_mfma_f32_32x32x16_bf16 v[18:33], v[46:49], v[152:155], v[18:33]
	s_waitcnt lgkmcnt(4)
	v_mfma_f32_32x32x16_bf16 v[18:33], v[50:53], v[148:151], v[18:33]
	s_waitcnt lgkmcnt(3)
	v_mfma_f32_32x32x16_bf16 v[18:33], v[54:57], v[144:147], v[18:33]
	s_waitcnt lgkmcnt(2)
	v_mfma_f32_32x32x16_bf16 v[18:33], v[58:61], v[140:143], v[18:33]
	s_waitcnt lgkmcnt(1)
	v_mfma_f32_32x32x16_bf16 v[18:33], v[62:65], v[136:139], v[18:33]
	s_waitcnt lgkmcnt(0)
	v_mfma_f32_32x32x16_bf16 v[18:33], v[66:69], v[132:135], v[18:33]
	s_waitcnt vmcnt(0)
	ds_write_b128 v120, v[196:199] offset:8192
	ds_write_b128 v120, v[200:203] offset:8448
	s_waitcnt lgkmcnt(0)
	s_barrier
	v_add_co_u32_e32 v200, vcc, s0, v118
	s_mov_b32 s0, 0x30000
	s_nop 0
	v_addc_co_u32_e32 v201, vcc, 0, v119, vcc
	v_add_co_u32_e32 v196, vcc, s0, v118
	global_load_dwordx4 v[200:203], v[200:201], off
	s_nop 0
	v_addc_co_u32_e32 v197, vcc, 0, v119, vcc
	global_load_dwordx4 v[196:199], v[196:197], off
	ds_read_b128 v[50:53], v211 offset:8192
	ds_read_b128 v[58:61], v211 offset:9216
	ds_read_b128 v[62:65], v211 offset:10240
	ds_read_b128 v[66:69], v211 offset:11264
	ds_read_b128 v[70:73], v211 offset:12288
	ds_read_b128 v[74:77], v211 offset:13312
	s_waitcnt lgkmcnt(5)
	v_mfma_f32_32x32x16_bf16 v[34:49], v[50:53], v[114:117], 0
	ds_read_b128 v[78:81], v211 offset:14336
	s_waitcnt lgkmcnt(5)
	v_mfma_f32_32x32x16_bf16 v[34:49], v[58:61], v[188:191], v[34:49]
	ds_read_b128 v[82:85], v211 offset:15360
	s_waitcnt lgkmcnt(5)
	v_mfma_f32_32x32x16_bf16 v[34:49], v[62:65], v[184:187], v[34:49]
	ds_read_b128 v[50:53], v211 offset:16384
	s_waitcnt lgkmcnt(5)
	v_mfma_f32_32x32x16_bf16 v[34:49], v[66:69], v[180:183], v[34:49]
	ds_read_b128 v[58:61], v211 offset:17408
	s_waitcnt lgkmcnt(5)
	v_mfma_f32_32x32x16_bf16 v[34:49], v[70:73], v[176:179], v[34:49]
	ds_read_b128 v[62:65], v211 offset:18432
	s_waitcnt lgkmcnt(5)
	v_mfma_f32_32x32x16_bf16 v[34:49], v[74:77], v[172:175], v[34:49]
	ds_read_b128 v[66:69], v211 offset:19456
	s_waitcnt lgkmcnt(5)
	v_mfma_f32_32x32x16_bf16 v[34:49], v[78:81], v[168:171], v[34:49]
	ds_read_b128 v[70:73], v211 offset:20480
	s_waitcnt lgkmcnt(5)
	v_mfma_f32_32x32x16_bf16 v[34:49], v[82:85], v[164:167], v[34:49]
	ds_read_b128 v[74:77], v211 offset:21504
	s_waitcnt lgkmcnt(5)
	v_mfma_f32_32x32x16_bf16 v[34:49], v[50:53], v[160:163], v[34:49]
	ds_read_b128 v[78:81], v211 offset:22528
	s_waitcnt lgkmcnt(5)
	v_mfma_f32_32x32x16_bf16 v[34:49], v[58:61], v[156:159], v[34:49]
	ds_read_b128 v[82:85], v211 offset:23552
	s_waitcnt lgkmcnt(5)
	v_mfma_f32_32x32x16_bf16 v[34:49], v[62:65], v[152:155], v[34:49]
	s_waitcnt lgkmcnt(4)
	v_mfma_f32_32x32x16_bf16 v[34:49], v[66:69], v[148:151], v[34:49]
	s_waitcnt lgkmcnt(3)
	v_mfma_f32_32x32x16_bf16 v[34:49], v[70:73], v[144:147], v[34:49]
	s_waitcnt lgkmcnt(2)
	v_mfma_f32_32x32x16_bf16 v[34:49], v[74:77], v[140:143], v[34:49]
	s_waitcnt lgkmcnt(1)
	v_mfma_f32_32x32x16_bf16 v[34:49], v[78:81], v[136:139], v[34:49]
	s_waitcnt lgkmcnt(0)
	v_mfma_f32_32x32x16_bf16 v[34:49], v[82:85], v[132:135], v[34:49]
	s_waitcnt vmcnt(0)
	ds_write_b128 v120, v[196:199] offset:24576
	ds_write_b128 v120, v[200:203] offset:24832
	s_waitcnt lgkmcnt(0)
	s_barrier
; #define LAS __attribute__((address_space(3)))
; __device__ __forceinline__ void attn_wg_unit(const Args& args, int l, int u, LAS unsigned char* lds, int tid_in) {
;     ...
;     for (int kt = 0; kt < 8; ++kt) {
;         if (kt < 7) { s0 = *(const u32x4*)(ksrc + (size_t)(32 * (kt + 1)) * MW); s1 = *(const u32x4*)(ksrc + (size_t)(32 * (kt + 1) + 16) * MW); }
;         else { s0 = *(const u32x4*)(vsrc); s1 = *(const u32x4*)(vsrc + 8); }
;         const LAS unsigned char* cb = buf + (kt & 1) * 16384 + lane * 16;
;         f32x16 acc;
; #pragma unroll
;         for (int i = 0; i < 16; ++i) acc[i] = 0.f;
; #pragma unroll
;         for (int ks = 0; ks < 16; ++ks) { const bf16x8 kf = *(const LAS bf16x8*)(cb + ks * 1024); acc = __builtin_amdgcn_mfma_f32_32x32x16_bf16(kf, qf[ks], acc, 0, 0, 0); }
;         st[kt] = acc;
;         LAS unsigned char* nb = buf + ((kt + 1) & 1) * 16384;
;         if (kt < 7) { *(LAS u32x4*)(nb + kdst) = s0; *(LAS u32x4*)(nb + kdst + 256) = s1; }
;         else { *(LAS u32x4*)(nb + vdst) = (u32x4){s0.x, s0.y, s1.x, s1.y}; *(LAS u32x4*)(nb + vdst + 512) = (u32x4){s0.z, s0.w, s1.z, s1.w}; }
;         __syncthreads();
;     }
	s_mov_b32 s0, 0x48000
	v_add_co_u32_e32 v200, vcc, s0, v118
	s_mov_b32 s0, 0x58000
	s_nop 0
	v_addc_co_u32_e32 v201, vcc, 0, v119, vcc
	v_add_co_u32_e32 v196, vcc, s21, v118
	global_load_dwordx4 v[200:203], v[200:201], off
	s_nop 0
	v_addc_co_u32_e32 v197, vcc, 0, v119, vcc
	global_load_dwordx4 v[196:199], v[196:197], off
	ds_read_b128 v[66:69], v211 offset:24576
	ds_read_b128 v[74:77], v211 offset:25600
	ds_read_b128 v[78:81], v211 offset:26624
	ds_read_b128 v[82:85], v211 offset:27648
	ds_read_b128 v[86:89], v211 offset:28672
	ds_read_b128 v[90:93], v211 offset:29696
	s_waitcnt lgkmcnt(5)
	v_mfma_f32_32x32x16_bf16 v[50:65], v[66:69], v[114:117], 0
	ds_read_b128 v[94:97], v211 offset:30720
	s_waitcnt lgkmcnt(5)
	v_mfma_f32_32x32x16_bf16 v[50:65], v[74:77], v[188:191], v[50:65]
	ds_read_b128 v[98:101], v211 offset:31744
	s_waitcnt lgkmcnt(5)
	v_mfma_f32_32x32x16_bf16 v[50:65], v[78:81], v[184:187], v[50:65]
	ds_read_b128 v[66:69], v211 offset:32768
	s_waitcnt lgkmcnt(5)
	v_mfma_f32_32x32x16_bf16 v[50:65], v[82:85], v[180:183], v[50:65]
	ds_read_b128 v[74:77], v211 offset:33792
	s_waitcnt lgkmcnt(5)
	v_mfma_f32_32x32x16_bf16 v[50:65], v[86:89], v[176:179], v[50:65]
	ds_read_b128 v[78:81], v211 offset:34816
	s_waitcnt lgkmcnt(5)
	v_mfma_f32_32x32x16_bf16 v[50:65], v[90:93], v[172:175], v[50:65]
	ds_read_b128 v[82:85], v211 offset:35840
	s_waitcnt lgkmcnt(5)
	v_mfma_f32_32x32x16_bf16 v[50:65], v[94:97], v[168:171], v[50:65]
	ds_read_b128 v[86:89], v211 offset:36864
	s_waitcnt lgkmcnt(5)
	v_mfma_f32_32x32x16_bf16 v[50:65], v[98:101], v[164:167], v[50:65]
	ds_read_b128 v[90:93], v211 offset:37888
	s_waitcnt lgkmcnt(5)
	v_mfma_f32_32x32x16_bf16 v[50:65], v[66:69], v[160:163], v[50:65]
	ds_read_b128 v[94:97], v211 offset:38912
	s_waitcnt lgkmcnt(5)
	v_mfma_f32_32x32x16_bf16 v[50:65], v[74:77], v[156:159], v[50:65]
	ds_read_b128 v[98:101], v211 offset:39936
	s_waitcnt lgkmcnt(5)
	v_mfma_f32_32x32x16_bf16 v[50:65], v[78:81], v[152:155], v[50:65]
	s_waitcnt lgkmcnt(4)
	v_mfma_f32_32x32x16_bf16 v[50:65], v[82:85], v[148:151], v[50:65]
	s_waitcnt lgkmcnt(3)
	v_mfma_f32_32x32x16_bf16 v[50:65], v[86:89], v[144:147], v[50:65]
	s_waitcnt lgkmcnt(2)
	v_mfma_f32_32x32x16_bf16 v[50:65], v[90:93], v[140:143], v[50:65]
	s_waitcnt lgkmcnt(1)
	v_mfma_f32_32x32x16_bf16 v[50:65], v[94:97], v[136:139], v[50:65]
	s_waitcnt lgkmcnt(0)
	v_mfma_f32_32x32x16_bf16 v[50:65], v[98:101], v[132:135], v[50:65]
	s_waitcnt vmcnt(0)
	ds_write_b128 v120, v[196:199] offset:8192
	ds_write_b128 v120, v[200:203] offset:8448
	s_waitcnt lgkmcnt(0)
	s_barrier
	v_add_co_u32_e32 v200, vcc, s0, v118
	s_mov_b32 s0, 0x50000
	s_nop 0
	v_addc_co_u32_e32 v201, vcc, 0, v119, vcc
	v_add_co_u32_e32 v196, vcc, s0, v118
	global_load_dwordx4 v[200:203], v[200:201], off
	s_nop 0
	v_addc_co_u32_e32 v197, vcc, 0, v119, vcc
	global_load_dwordx4 v[196:199], v[196:197], off
	ds_read_b128 v[82:85], v211 offset:8192
	ds_read_b128 v[90:93], v211 offset:9216
	ds_read_b128 v[94:97], v211 offset:10240
	ds_read_b128 v[98:101], v211 offset:11264
	ds_read_b128 v[102:105], v211 offset:12288
	ds_read_b128 v[106:109], v211 offset:13312
	s_waitcnt lgkmcnt(5)
	v_mfma_f32_32x32x16_bf16 v[66:81], v[82:85], v[114:117], 0
	ds_read_b128 v[110:113], v211 offset:14336
	s_waitcnt lgkmcnt(5)
	v_mfma_f32_32x32x16_bf16 v[66:81], v[90:93], v[188:191], v[66:81]
	ds_read_b128 v[122:125], v211 offset:15360
	s_waitcnt lgkmcnt(5)
	v_mfma_f32_32x32x16_bf16 v[66:81], v[94:97], v[184:187], v[66:81]
	ds_read_b128 v[82:85], v211 offset:16384
	s_waitcnt lgkmcnt(5)
	v_mfma_f32_32x32x16_bf16 v[66:81], v[98:101], v[180:183], v[66:81]
	ds_read_b128 v[90:93], v211 offset:17408
	s_waitcnt lgkmcnt(5)
	v_mfma_f32_32x32x16_bf16 v[66:81], v[102:105], v[176:179], v[66:81]
	ds_read_b128 v[94:97], v211 offset:18432
	s_waitcnt lgkmcnt(5)
	v_mfma_f32_32x32x16_bf16 v[66:81], v[106:109], v[172:175], v[66:81]
	ds_read_b128 v[98:101], v211 offset:19456
	s_waitcnt lgkmcnt(5)
	v_mfma_f32_32x32x16_bf16 v[66:81], v[110:113], v[168:171], v[66:81]
	ds_read_b128 v[102:105], v211 offset:20480
	s_waitcnt lgkmcnt(5)
	v_mfma_f32_32x32x16_bf16 v[66:81], v[122:125], v[164:167], v[66:81]
	ds_read_b128 v[106:109], v211 offset:21504
	s_waitcnt lgkmcnt(5)
	v_mfma_f32_32x32x16_bf16 v[66:81], v[82:85], v[160:163], v[66:81]
	ds_read_b128 v[110:113], v211 offset:22528
	s_waitcnt lgkmcnt(5)
	v_mfma_f32_32x32x16_bf16 v[66:81], v[90:93], v[156:159], v[66:81]
	ds_read_b128 v[122:125], v211 offset:23552
	s_waitcnt lgkmcnt(5)
	v_mfma_f32_32x32x16_bf16 v[66:81], v[94:97], v[152:155], v[66:81]
	s_waitcnt lgkmcnt(4)
	v_mfma_f32_32x32x16_bf16 v[66:81], v[98:101], v[148:151], v[66:81]
	s_waitcnt lgkmcnt(3)
	v_mfma_f32_32x32x16_bf16 v[66:81], v[102:105], v[144:147], v[66:81]
	s_waitcnt lgkmcnt(2)
	v_mfma_f32_32x32x16_bf16 v[66:81], v[106:109], v[140:143], v[66:81]
	s_waitcnt lgkmcnt(1)
	v_mfma_f32_32x32x16_bf16 v[66:81], v[110:113], v[136:139], v[66:81]
	s_waitcnt lgkmcnt(0)
	v_mfma_f32_32x32x16_bf16 v[66:81], v[122:125], v[132:135], v[66:81]
	s_waitcnt vmcnt(0)
	ds_write_b128 v120, v[196:199] offset:24576
	ds_write_b128 v120, v[200:203] offset:24832
	s_waitcnt lgkmcnt(0)
	s_barrier
; #define LAS __attribute__((address_space(3)))
; __device__ __forceinline__ void attn_wg_unit(const Args& args, int l, int u, LAS unsigned char* lds, int tid_in) {
;     ...
;     for (int kt = 0; kt < 8; ++kt) {
;         if (kt < 7) { s0 = *(const u32x4*)(ksrc + (size_t)(32 * (kt + 1)) * MW); s1 = *(const u32x4*)(ksrc + (size_t)(32 * (kt + 1) + 16) * MW); }
;         else { s0 = *(const u32x4*)(vsrc); s1 = *(const u32x4*)(vsrc + 8); }
;         const LAS unsigned char* cb = buf + (kt & 1) * 16384 + lane * 16;
;         f32x16 acc;
; #pragma unroll
;         for (int i = 0; i < 16; ++i) acc[i] = 0.f;
; #pragma unroll
;         for (int ks = 0; ks < 16; ++ks) { const bf16x8 kf = *(const LAS bf16x8*)(cb + ks * 1024); acc = __builtin_amdgcn_mfma_f32_32x32x16_bf16(kf, qf[ks], acc, 0, 0, 0); }
;         st[kt] = acc;
;         LAS unsigned char* nb = buf + ((kt + 1) & 1) * 16384;
;         if (kt < 7) { *(LAS u32x4*)(nb + kdst) = s0; *(LAS u32x4*)(nb + kdst + 256) = s1; }
;         else { *(LAS u32x4*)(nb + vdst) = (u32x4){s0.x, s0.y, s1.x, s1.y}; *(LAS u32x4*)(nb + vdst + 512) = (u32x4){s0.z, s0.w, s1.z, s1.w}; }
;         __syncthreads();
;     }
	s_mov_b32 s0, 0x68000
	v_add_co_u32_e32 v200, vcc, s0, v118
	s_mov_b32 s0, 0x78000
	s_nop 0
	v_addc_co_u32_e32 v201, vcc, 0, v119, vcc
	v_add_co_u32_e32 v196, vcc, s22, v118
	global_load_dwordx4 v[200:203], v[200:201], off
	s_nop 0
	v_addc_co_u32_e32 v197, vcc, 0, v119, vcc
	global_load_dwordx4 v[196:199], v[196:197], off
	ds_read_b128 v[98:101], v211 offset:24576
	ds_read_b128 v[106:109], v211 offset:25600
	ds_read_b128 v[110:113], v211 offset:26624
	ds_read_b128 v[122:125], v211 offset:27648
	ds_read_b128 v[126:129], v211 offset:28672
	ds_read_b128 v[192:195], v211 offset:29696
	s_waitcnt lgkmcnt(5)
	v_mfma_f32_32x32x16_bf16 v[82:97], v[98:101], v[114:117], 0
	ds_read_b128 v[98:101], v211 offset:30720
	s_waitcnt lgkmcnt(5)
	v_mfma_f32_32x32x16_bf16 v[82:97], v[106:109], v[188:191], v[82:97]
	ds_read_b128 v[106:109], v211 offset:31744
	s_waitcnt lgkmcnt(5)
	v_mfma_f32_32x32x16_bf16 v[82:97], v[110:113], v[184:187], v[82:97]
	ds_read_b128 v[110:113], v211 offset:32768
	s_waitcnt lgkmcnt(5)
	v_mfma_f32_32x32x16_bf16 v[82:97], v[122:125], v[180:183], v[82:97]
	ds_read_b128 v[122:125], v211 offset:33792
	s_waitcnt lgkmcnt(5)
	v_mfma_f32_32x32x16_bf16 v[82:97], v[126:129], v[176:179], v[82:97]
	ds_read_b128 v[126:129], v211 offset:34816
	s_waitcnt lgkmcnt(5)
	v_mfma_f32_32x32x16_bf16 v[82:97], v[192:195], v[172:175], v[82:97]
	ds_read_b128 v[192:195], v211 offset:35840
	s_waitcnt lgkmcnt(5)
	v_mfma_f32_32x32x16_bf16 v[82:97], v[98:101], v[168:171], v[82:97]
	ds_read_b128 v[98:101], v211 offset:36864
	s_waitcnt lgkmcnt(5)
	v_mfma_f32_32x32x16_bf16 v[82:97], v[106:109], v[164:167], v[82:97]
	ds_read_b128 v[106:109], v211 offset:37888
	s_waitcnt lgkmcnt(5)
	v_mfma_f32_32x32x16_bf16 v[82:97], v[110:113], v[160:163], v[82:97]
	ds_read_b128 v[110:113], v211 offset:38912
	s_waitcnt lgkmcnt(5)
	v_mfma_f32_32x32x16_bf16 v[82:97], v[122:125], v[156:159], v[82:97]
	ds_read_b128 v[122:125], v211 offset:39936
	s_waitcnt lgkmcnt(5)
	v_mfma_f32_32x32x16_bf16 v[82:97], v[126:129], v[152:155], v[82:97]
	s_waitcnt lgkmcnt(4)
	v_mfma_f32_32x32x16_bf16 v[82:97], v[192:195], v[148:151], v[82:97]
	s_waitcnt lgkmcnt(3)
	v_mfma_f32_32x32x16_bf16 v[82:97], v[98:101], v[144:147], v[82:97]
	s_waitcnt lgkmcnt(2)
	v_mfma_f32_32x32x16_bf16 v[82:97], v[106:109], v[140:143], v[82:97]
	s_waitcnt lgkmcnt(1)
	v_mfma_f32_32x32x16_bf16 v[82:97], v[110:113], v[136:139], v[82:97]
	s_waitcnt lgkmcnt(0)
	v_mfma_f32_32x32x16_bf16 v[82:97], v[122:125], v[132:135], v[82:97]
	s_waitcnt vmcnt(0)
	ds_write_b128 v120, v[196:199] offset:8192
	ds_write_b128 v120, v[200:203] offset:8448
	s_waitcnt lgkmcnt(0)
	s_barrier
	v_add_co_u32_e32 v200, vcc, s0, v118
	s_mov_b32 s0, 0x70000
	s_nop 0
	v_addc_co_u32_e32 v201, vcc, 0, v119, vcc
	v_add_co_u32_e32 v118, vcc, s0, v118
	global_load_dwordx4 v[200:203], v[200:201], off
	s_nop 0
	v_addc_co_u32_e32 v119, vcc, 0, v119, vcc
	global_load_dwordx4 v[196:199], v[118:119], off
	ds_read_b128 v[122:125], v211 offset:8192
	ds_read_b128 v[192:195], v211 offset:9216
	s_waitcnt lgkmcnt(1)
	v_mfma_f32_32x32x16_bf16 v[98:113], v[122:125], v[114:117], 0
	ds_read_b128 v[122:125], v211 offset:10240
	s_waitcnt lgkmcnt(1)
	v_mfma_f32_32x32x16_bf16 v[98:113], v[192:195], v[188:191], v[98:113]
	ds_read_b128 v[192:195], v211 offset:11264
	s_waitcnt lgkmcnt(1)
	v_mfma_f32_32x32x16_bf16 v[98:113], v[122:125], v[184:187], v[98:113]
	ds_read_b128 v[122:125], v211 offset:12288
	s_waitcnt lgkmcnt(1)
	v_mfma_f32_32x32x16_bf16 v[98:113], v[192:195], v[180:183], v[98:113]
	ds_read_b128 v[192:195], v211 offset:13312
	s_waitcnt lgkmcnt(1)
	v_mfma_f32_32x32x16_bf16 v[98:113], v[122:125], v[176:179], v[98:113]
	ds_read_b128 v[122:125], v211 offset:14336
	s_waitcnt lgkmcnt(1)
	v_mfma_f32_32x32x16_bf16 v[98:113], v[192:195], v[172:175], v[98:113]
	ds_read_b128 v[192:195], v211 offset:15360
	s_waitcnt lgkmcnt(1)
	v_mfma_f32_32x32x16_bf16 v[98:113], v[122:125], v[168:171], v[98:113]
	ds_read_b128 v[122:125], v211 offset:16384
	s_waitcnt lgkmcnt(1)
	v_mfma_f32_32x32x16_bf16 v[98:113], v[192:195], v[164:167], v[98:113]
	ds_read_b128 v[192:195], v211 offset:17408
	s_waitcnt lgkmcnt(1)
	v_mfma_f32_32x32x16_bf16 v[98:113], v[122:125], v[160:163], v[98:113]
	ds_read_b128 v[122:125], v211 offset:18432
	s_waitcnt lgkmcnt(1)
	v_mfma_f32_32x32x16_bf16 v[98:113], v[192:195], v[156:159], v[98:113]
	ds_read_b128 v[192:195], v211 offset:19456
	s_waitcnt lgkmcnt(1)
	v_mfma_f32_32x32x16_bf16 v[98:113], v[122:125], v[152:155], v[98:113]
	ds_read_b128 v[122:125], v211 offset:20480
	s_waitcnt lgkmcnt(1)
	v_mfma_f32_32x32x16_bf16 v[98:113], v[192:195], v[148:151], v[98:113]
	ds_read_b128 v[192:195], v211 offset:21504
	s_waitcnt lgkmcnt(1)
	v_mfma_f32_32x32x16_bf16 v[98:113], v[122:125], v[144:147], v[98:113]
	ds_read_b128 v[122:125], v211 offset:22528
	s_waitcnt lgkmcnt(1)
	v_mfma_f32_32x32x16_bf16 v[98:113], v[192:195], v[140:143], v[98:113]
	ds_read_b128 v[192:195], v211 offset:23552
	s_waitcnt lgkmcnt(1)
	v_mfma_f32_32x32x16_bf16 v[98:113], v[122:125], v[136:139], v[98:113]
	s_waitcnt lgkmcnt(0)
	v_mfma_f32_32x32x16_bf16 v[98:113], v[192:195], v[132:135], v[98:113]
	s_waitcnt vmcnt(0)
	ds_write_b128 v120, v[196:199] offset:24576
	ds_write_b128 v120, v[200:203] offset:24832
	s_waitcnt lgkmcnt(0)
	s_barrier
; #define LAS __attribute__((address_space(3)))
; __device__ __forceinline__ void attn_wg_unit(const Args& args, int l, int u, LAS unsigned char* lds, int tid_in) {
;     ...
;         else { s0 = *(const u32x4*)(vsrc); s1 = *(const u32x4*)(vsrc + 8); }
;         const LAS unsigned char* cb = buf + (kt & 1) * 16384 + lane * 16;
;         f32x16 acc;
; #pragma unroll
;         for (int i = 0; i < 16; ++i) acc[i] = 0.f;
; #pragma unroll
;         for (int ks = 0; ks < 16; ++ks) { const bf16x8 kf = *(const LAS bf16x8*)(cb + ks * 1024); acc = __builtin_amdgcn_mfma_f32_32x32x16_bf16(kf, qf[ks], acc, 0, 0, 0); }
;         st[kt] = acc;
;         LAS unsigned char* nb = buf + ((kt + 1) & 1) * 16384;
;         if (kt < 7) { *(LAS u32x4*)(nb + kdst) = s0; *(LAS u32x4*)(nb + kdst + 256) = s1; }
;         else { *(LAS u32x4*)(nb + vdst) = (u32x4){s0.x, s0.y, s1.x, s1.y}; *(LAS u32x4*)(nb + vdst + 512) = (u32x4){s0.z, s0.w, s1.z, s1.w}; }
;         __syncthreads();
;     }
;     float mx = st[0][0];
; #pragma unroll
;     for (int kt = 0; kt < 8; ++kt)
; #pragma unroll
;         for (int i = 0; i < 16; ++i) mx = fmaxf(mx, st[kt][i]);
;     mx = fmaxf(mx, __shfl_xor(mx, 32));
	ds_read_b128 v[118:121], v211 offset:24576
	ds_read_b128 v[194:197], v211 offset:25600
	ds_read_b128 v[198:201], v211 offset:26624
	s_waitcnt lgkmcnt(2)
	v_mfma_f32_32x32x16_bf16 v[114:129], v[118:121], v[114:117], 0
	s_waitcnt lgkmcnt(1)
	v_mfma_f32_32x32x16_bf16 v[114:129], v[194:197], v[188:191], v[114:129]
	ds_read_b128 v[194:197], v211 offset:27648
	ds_read_b128 v[188:191], v211 offset:28672
	s_waitcnt lgkmcnt(2)
	v_mfma_f32_32x32x16_bf16 v[114:129], v[198:201], v[184:187], v[114:129]
	ds_read_b128 v[198:201], v211 offset:29696
	ds_read_b128 v[184:187], v211 offset:30720
	s_waitcnt lgkmcnt(3)
	v_mfma_f32_32x32x16_bf16 v[114:129], v[194:197], v[180:183], v[114:129]
	ds_read_b128 v[194:197], v211 offset:31744
	s_waitcnt lgkmcnt(3)
	v_mfma_f32_32x32x16_bf16 v[114:129], v[188:191], v[176:179], v[114:129]
	ds_read_b128 v[180:183], v211 offset:32768
	s_waitcnt lgkmcnt(3)
	v_mfma_f32_32x32x16_bf16 v[114:129], v[198:201], v[172:175], v[114:129]
	ds_read_b128 v[188:191], v211 offset:33792
	s_waitcnt lgkmcnt(3)
	v_mfma_f32_32x32x16_bf16 v[114:129], v[184:187], v[168:171], v[114:129]
	ds_read_b128 v[176:179], v211 offset:34816
	s_waitcnt lgkmcnt(3)
	v_mfma_f32_32x32x16_bf16 v[114:129], v[194:197], v[164:167], v[114:129]
	ds_read_b128 v[198:201], v211 offset:35840
	s_waitcnt lgkmcnt(3)
	v_mfma_f32_32x32x16_bf16 v[114:129], v[180:183], v[160:163], v[114:129]
	ds_read_b128 v[172:175], v211 offset:36864
	s_waitcnt lgkmcnt(3)
	v_mfma_f32_32x32x16_bf16 v[114:129], v[188:191], v[156:159], v[114:129]
	ds_read_b128 v[184:187], v211 offset:37888
	s_waitcnt lgkmcnt(3)
	v_mfma_f32_32x32x16_bf16 v[114:129], v[176:179], v[152:155], v[114:129]
	ds_read_b128 v[168:171], v211 offset:38912
	s_waitcnt lgkmcnt(3)
	v_mfma_f32_32x32x16_bf16 v[114:129], v[198:201], v[148:151], v[114:129]
	ds_read_b128 v[194:197], v211 offset:39936
	s_waitcnt lgkmcnt(3)
	v_mfma_f32_32x32x16_bf16 v[114:129], v[172:175], v[144:147], v[114:129]
	s_waitcnt lgkmcnt(2)
	v_mfma_f32_32x32x16_bf16 v[114:129], v[184:187], v[140:143], v[114:129]
	s_waitcnt lgkmcnt(1)
	v_mfma_f32_32x32x16_bf16 v[114:129], v[168:171], v[136:139], v[114:129]
	s_waitcnt lgkmcnt(0)
	v_mfma_f32_32x32x16_bf16 v[114:129], v[194:197], v[132:135], v[114:129]
	global_load_dwordx4 v[132:135], v[214:215], off offset:16
	global_load_dwordx4 v[136:139], v[214:215], off
	s_waitcnt vmcnt(1)
	v_mov_b32_e32 v142, v132
	v_mov_b32_e32 v143, v133
	s_waitcnt vmcnt(0)
	v_mov_b32_e32 v132, v138
	v_mov_b32_e32 v133, v139
	ds_write_b128 v216, v[132:135] offset:8704
	v_max_f32_e32 v132, v3, v3
	v_max_f32_e32 v133, v2, v2
	v_max_f32_e32 v132, v133, v132
	v_max3_f32 v132, v132, v4, v5
	v_max3_f32 v132, v132, v6, v7
	v_max3_f32 v132, v132, v8, v9
	v_max3_f32 v132, v132, v10, v11
	v_max3_f32 v132, v132, v12, v13
	v_max3_f32 v132, v132, v14, v15
	v_max3_f32 v132, v132, v16, v17
	v_max3_f32 v132, v132, v18, v19
	v_max3_f32 v132, v132, v20, v21
	v_max3_f32 v132, v132, v22, v23
	v_max3_f32 v132, v132, v24, v25
	v_max3_f32 v132, v132, v26, v27
	v_max3_f32 v132, v132, v28, v29
	v_max3_f32 v132, v132, v30, v31
	v_max3_f32 v132, v132, v32, v33
	v_max3_f32 v132, v132, v34, v35
	v_max3_f32 v132, v132, v36, v37
	v_max3_f32 v132, v132, v38, v39
	v_max3_f32 v132, v132, v40, v41
	v_max3_f32 v132, v132, v42, v43
	v_max3_f32 v132, v132, v44, v45
	v_max3_f32 v132, v132, v46, v47
	v_max3_f32 v132, v132, v48, v49
	v_max3_f32 v132, v132, v50, v51
	v_max3_f32 v132, v132, v52, v53
	v_max3_f32 v132, v132, v54, v55
	v_max3_f32 v132, v132, v56, v57
	v_max3_f32 v132, v132, v58, v59
	v_max3_f32 v132, v132, v60, v61
	v_max3_f32 v132, v132, v62, v63
	v_max3_f32 v132, v132, v64, v65
	v_max3_f32 v132, v132, v66, v67
	v_max3_f32 v132, v132, v68, v69
	v_max3_f32 v132, v132, v70, v71
	v_max3_f32 v132, v132, v72, v73
	v_max3_f32 v132, v132, v74, v75
	v_max3_f32 v132, v132, v76, v77
	v_max3_f32 v132, v132, v78, v79
	v_max3_f32 v132, v132, v80, v81
	v_max3_f32 v132, v132, v82, v83
	v_max3_f32 v132, v132, v84, v85
	v_max3_f32 v132, v132, v86, v87
	v_max3_f32 v132, v132, v88, v89
	v_max3_f32 v132, v132, v90, v91
	v_max3_f32 v132, v132, v92, v93
	v_max3_f32 v132, v132, v94, v95
	v_max3_f32 v132, v132, v96, v97
	v_max3_f32 v132, v132, v98, v99
	v_max3_f32 v132, v132, v100, v101
	v_max3_f32 v132, v132, v102, v103
	v_max3_f32 v132, v132, v104, v105
	v_max3_f32 v132, v132, v106, v107
	v_max3_f32 v132, v132, v108, v109
	v_max3_f32 v132, v132, v110, v111
	v_max3_f32 v132, v132, v112, v113
	v_max3_f32 v132, v132, v114, v115
	v_max3_f32 v132, v132, v116, v117
	v_max3_f32 v132, v132, v118, v119
	v_max3_f32 v132, v132, v120, v121
	v_and_b32_e32 v134, 64, v204
	v_max3_f32 v132, v132, v122, v123
	v_xor_b32_e32 v133, 32, v204
	v_add_u32_e32 v134, 64, v134
	v_max3_f32 v132, v132, v124, v125
	v_cmp_lt_i32_e32 vcc, v133, v134
	v_max3_f32 v132, v132, v126, v127
	v_max3_f32 v132, v132, v128, v129
	v_cndmask_b32_e32 v133, v204, v133, vcc
	v_lshlrev_b32_e32 v196, 2, v133
	ds_bpermute_b32 v133, v196, v132
	v_mov_b32_e32 v140, v136
	v_mov_b32_e32 v141, v137
	ds_write_b128 v216, v[140:143] offset:8192
	s_waitcnt lgkmcnt(0)
; __device__ __forceinline__ unsigned cvtpk(float lo, float hi) { f32x2 v = {lo, hi}; bf16x2_t b = __builtin_convertvector(v, bf16x2_t); return __builtin_bit_cast(unsigned, b); }
; __device__ __forceinline__ void attn_wg_unit(const Args& args, int l, int u, LAS unsigned char* lds, int tid_in) {
;     ...
;     float sum = 0.f;
;     bf16x8 pf[8][2];
; #pragma unroll
;     for (int kt = 0; kt < 8; ++kt) {
; #pragma unroll
;         for (int i = 0; i < 16; ++i) { const float e = __builtin_amdgcn_exp2f(st[kt][i] - mx); st[kt][i] = e; sum += e; }
; #pragma unroll
;         for (int s = 0; s < 2; ++s) { u32x4 w; w.x = cvtpk(st[kt][8 * s + 0], st[kt][8 * s + 1]); w.y = cvtpk(st[kt][8 * s + 2], st[kt][8 * s + 3]); w.z = cvtpk(st[kt][8 * s + 4], st[kt][8 * s + 5]); w.w = cvtpk(st[kt][8 * s + 6], st[kt][8 * s + 7]);
;             pf[kt][s] = __builtin_bit_cast(bf16x8, w); }
;     }
	v_max_f32_e32 v133, v133, v133
	v_max_f32_e32 v140, v132, v133
	v_sub_f32_e32 v2, v2, v140
	v_sub_f32_e32 v3, v3, v140
	v_exp_f32_e32 v2, v2
	v_exp_f32_e32 v3, v3
	v_sub_f32_e32 v4, v4, v140
	v_exp_f32_e32 v4, v4
	v_sub_f32_e32 v5, v5, v140
	v_exp_f32_e32 v5, v5
	v_sub_f32_e32 v6, v6, v140
	v_exp_f32_e32 v6, v6
	v_sub_f32_e32 v7, v7, v140
	v_cvt_pk_bf16_f32 v192, v2, v3
	v_add_f32_e32 v2, 0, v2
	v_exp_f32_e32 v7, v7
	v_sub_f32_e32 v8, v8, v140
	v_add_f32_e32 v2, v3, v2
	v_exp_f32_e32 v8, v8
	v_sub_f32_e32 v9, v9, v140
	v_add_f32_e32 v2, v4, v2
	v_exp_f32_e32 v9, v9
	v_sub_f32_e32 v10, v10, v140
	v_add_f32_e32 v2, v5, v2
	v_exp_f32_e32 v10, v10
	v_sub_f32_e32 v11, v11, v140
	v_add_f32_e32 v2, v6, v2
	v_exp_f32_e32 v11, v11
	v_sub_f32_e32 v12, v12, v140
	v_add_f32_e32 v2, v7, v2
	v_exp_f32_e32 v12, v12
	v_sub_f32_e32 v13, v13, v140
	v_add_f32_e32 v2, v8, v2
	v_exp_f32_e32 v13, v13
	v_sub_f32_e32 v14, v14, v140
	v_add_f32_e32 v2, v9, v2
	v_exp_f32_e32 v14, v14
	v_sub_f32_e32 v15, v15, v140
	v_add_f32_e32 v2, v10, v2
	v_exp_f32_e32 v15, v15
	v_sub_f32_e32 v16, v16, v140
	v_add_f32_e32 v2, v11, v2
	v_exp_f32_e32 v16, v16
	v_sub_f32_e32 v17, v17, v140
	v_add_f32_e32 v2, v12, v2
	v_exp_f32_e32 v17, v17
	v_add_f32_e32 v2, v13, v2
	v_sub_f32_e32 v3, v18, v140
	v_cvt_pk_bf16_f32 v193, v4, v5
	v_add_f32_e32 v2, v14, v2
	v_exp_f32_e32 v3, v3
	v_sub_f32_e32 v4, v19, v140
	v_add_f32_e32 v2, v15, v2
	v_exp_f32_e32 v4, v4
	v_sub_f32_e32 v5, v20, v140
	v_cvt_pk_bf16_f32 v194, v6, v7
	v_add_f32_e32 v2, v16, v2
	v_exp_f32_e32 v5, v5
	v_sub_f32_e32 v6, v21, v140
	v_add_f32_e32 v2, v17, v2
	v_exp_f32_e32 v6, v6
	v_sub_f32_e32 v7, v22, v140
	v_cvt_pk_bf16_f32 v195, v8, v9
	v_exp_f32_e32 v7, v7
	v_sub_f32_e32 v8, v23, v140
	v_add_f32_e32 v2, v3, v2
	v_exp_f32_e32 v8, v8
	v_sub_f32_e32 v9, v24, v140
	v_add_f32_e32 v2, v4, v2
	v_cvt_pk_bf16_f32 v188, v10, v11
	v_exp_f32_e32 v9, v9
	v_sub_f32_e32 v10, v25, v140
	v_add_f32_e32 v2, v5, v2
	v_exp_f32_e32 v10, v10
	v_sub_f32_e32 v11, v26, v140
	v_add_f32_e32 v2, v6, v2
	v_cvt_pk_bf16_f32 v189, v12, v13
	v_exp_f32_e32 v11, v11
	v_sub_f32_e32 v12, v27, v140
	v_add_f32_e32 v2, v7, v2
	v_exp_f32_e32 v12, v12
	v_sub_f32_e32 v13, v28, v140
	v_add_f32_e32 v2, v8, v2
	v_cvt_pk_bf16_f32 v190, v14, v15
	v_exp_f32_e32 v13, v13
	v_sub_f32_e32 v14, v29, v140
	v_add_f32_e32 v2, v9, v2
	v_exp_f32_e32 v14, v14
	v_sub_f32_e32 v15, v30, v140
	v_add_f32_e32 v2, v10, v2
	v_cvt_pk_bf16_f32 v191, v16, v17
	v_exp_f32_e32 v15, v15
	v_sub_f32_e32 v16, v31, v140
	v_add_f32_e32 v2, v11, v2
	v_exp_f32_e32 v16, v16
	v_sub_f32_e32 v17, v32, v140
	v_add_f32_e32 v2, v12, v2
	v_exp_f32_e32 v17, v17
	v_sub_f32_e32 v18, v33, v140
	v_add_f32_e32 v2, v13, v2
	v_exp_f32_e32 v18, v18
	v_cvt_pk_bf16_f32 v184, v3, v4
	v_add_f32_e32 v2, v14, v2
	v_sub_f32_e32 v3, v34, v140
	v_add_f32_e32 v2, v15, v2
	v_exp_f32_e32 v3, v3
	v_sub_f32_e32 v4, v35, v140
	v_cvt_pk_bf16_f32 v185, v5, v6
	v_add_f32_e32 v2, v16, v2
	v_exp_f32_e32 v4, v4
	v_sub_f32_e32 v5, v36, v140
	v_add_f32_e32 v2, v17, v2
	v_exp_f32_e32 v5, v5
	v_sub_f32_e32 v6, v37, v140
	v_cvt_pk_bf16_f32 v186, v7, v8
	v_add_f32_e32 v2, v18, v2
	v_exp_f32_e32 v6, v6
	v_sub_f32_e32 v7, v38, v140
	v_exp_f32_e32 v7, v7
	v_sub_f32_e32 v8, v39, v140
	v_add_f32_e32 v2, v3, v2
	v_cvt_pk_bf16_f32 v187, v9, v10
	v_exp_f32_e32 v8, v8
	v_sub_f32_e32 v9, v40, v140
	v_add_f32_e32 v2, v4, v2
	v_exp_f32_e32 v9, v9
	v_sub_f32_e32 v10, v41, v140
	v_add_f32_e32 v2, v5, v2
	v_cvt_pk_bf16_f32 v180, v11, v12
	v_exp_f32_e32 v10, v10
	v_sub_f32_e32 v11, v42, v140
	v_add_f32_e32 v2, v6, v2
	v_exp_f32_e32 v11, v11
	v_sub_f32_e32 v12, v43, v140
	v_add_f32_e32 v2, v7, v2
	v_cvt_pk_bf16_f32 v181, v13, v14
	v_exp_f32_e32 v12, v12
	v_sub_f32_e32 v13, v44, v140
	v_add_f32_e32 v2, v8, v2
	v_exp_f32_e32 v13, v13
	v_sub_f32_e32 v14, v45, v140
	v_add_f32_e32 v2, v9, v2
	v_cvt_pk_bf16_f32 v182, v15, v16
	v_exp_f32_e32 v14, v14
	v_sub_f32_e32 v15, v46, v140
	v_add_f32_e32 v2, v10, v2
	v_exp_f32_e32 v15, v15
	v_sub_f32_e32 v16, v47, v140
	v_add_f32_e32 v2, v11, v2
	v_cvt_pk_bf16_f32 v183, v17, v18
	v_exp_f32_e32 v16, v16
	v_sub_f32_e32 v17, v48, v140
	v_add_f32_e32 v2, v12, v2
	v_exp_f32_e32 v17, v17
	v_sub_f32_e32 v18, v49, v140
	v_add_f32_e32 v2, v13, v2
	v_exp_f32_e32 v18, v18
	v_cvt_pk_bf16_f32 v176, v3, v4
	v_add_f32_e32 v2, v14, v2
	v_sub_f32_e32 v3, v50, v140
	v_add_f32_e32 v2, v15, v2
	v_exp_f32_e32 v3, v3
	v_sub_f32_e32 v4, v51, v140
	v_cvt_pk_bf16_f32 v177, v5, v6
	v_add_f32_e32 v2, v16, v2
	v_exp_f32_e32 v4, v4
	v_sub_f32_e32 v5, v52, v140
	v_add_f32_e32 v2, v17, v2
	v_exp_f32_e32 v5, v5
	v_sub_f32_e32 v6, v53, v140
	v_cvt_pk_bf16_f32 v178, v7, v8
	v_add_f32_e32 v2, v18, v2
	v_exp_f32_e32 v6, v6
	v_sub_f32_e32 v7, v54, v140
	v_exp_f32_e32 v7, v7
	v_sub_f32_e32 v8, v55, v140
	v_add_f32_e32 v2, v3, v2
	v_cvt_pk_bf16_f32 v179, v9, v10
	v_exp_f32_e32 v8, v8
	v_sub_f32_e32 v9, v56, v140
	v_add_f32_e32 v2, v4, v2
	v_exp_f32_e32 v9, v9
	v_sub_f32_e32 v10, v57, v140
	v_add_f32_e32 v2, v5, v2
	v_cvt_pk_bf16_f32 v172, v11, v12
	v_exp_f32_e32 v10, v10
	v_sub_f32_e32 v11, v58, v140
	v_add_f32_e32 v2, v6, v2
	v_exp_f32_e32 v11, v11
	v_sub_f32_e32 v12, v59, v140
	v_add_f32_e32 v2, v7, v2
	v_cvt_pk_bf16_f32 v173, v13, v14
	v_exp_f32_e32 v12, v12
	v_sub_f32_e32 v13, v60, v140
	v_add_f32_e32 v2, v8, v2
	v_exp_f32_e32 v13, v13
	v_sub_f32_e32 v14, v61, v140
	v_add_f32_e32 v2, v9, v2
	v_cvt_pk_bf16_f32 v174, v15, v16
	v_exp_f32_e32 v14, v14
	v_sub_f32_e32 v15, v62, v140
	v_add_f32_e32 v2, v10, v2
	v_exp_f32_e32 v15, v15
	v_sub_f32_e32 v16, v63, v140
	v_add_f32_e32 v2, v11, v2
	v_cvt_pk_bf16_f32 v175, v17, v18
	v_exp_f32_e32 v16, v16
	v_sub_f32_e32 v17, v64, v140
; __device__ __forceinline__ unsigned cvtpk(float lo, float hi) { f32x2 v = {lo, hi}; bf16x2_t b = __builtin_convertvector(v, bf16x2_t); return __builtin_bit_cast(unsigned, b); }
; __device__ __forceinline__ void attn_wg_unit(const Args& args, int l, int u, LAS unsigned char* lds, int tid_in) {
;     ...
;     float sum = 0.f;
;     bf16x8 pf[8][2];
; #pragma unroll
;     for (int kt = 0; kt < 8; ++kt) {
; #pragma unroll
;         for (int i = 0; i < 16; ++i) { const float e = __builtin_amdgcn_exp2f(st[kt][i] - mx); st[kt][i] = e; sum += e; }
; #pragma unroll
;         for (int s = 0; s < 2; ++s) { u32x4 w; w.x = cvtpk(st[kt][8 * s + 0], st[kt][8 * s + 1]); w.y = cvtpk(st[kt][8 * s + 2], st[kt][8 * s + 3]); w.z = cvtpk(st[kt][8 * s + 4], st[kt][8 * s + 5]); w.w = cvtpk(st[kt][8 * s + 6], st[kt][8 * s + 7]);
;             pf[kt][s] = __builtin_bit_cast(bf16x8, w); }
;     }
	v_add_f32_e32 v2, v12, v2
	v_exp_f32_e32 v17, v17
	v_sub_f32_e32 v18, v65, v140
	v_add_f32_e32 v2, v13, v2
	v_exp_f32_e32 v18, v18
	v_cvt_pk_bf16_f32 v168, v3, v4
	v_add_f32_e32 v2, v14, v2
	v_sub_f32_e32 v3, v66, v140
	v_add_f32_e32 v2, v15, v2
	v_exp_f32_e32 v3, v3
	v_sub_f32_e32 v4, v67, v140
	v_cvt_pk_bf16_f32 v169, v5, v6
	v_add_f32_e32 v2, v16, v2
	v_exp_f32_e32 v4, v4
	v_sub_f32_e32 v5, v68, v140
	v_add_f32_e32 v2, v17, v2
	v_exp_f32_e32 v5, v5
	v_sub_f32_e32 v6, v69, v140
	v_cvt_pk_bf16_f32 v170, v7, v8
	v_add_f32_e32 v2, v18, v2
	v_exp_f32_e32 v6, v6
	v_sub_f32_e32 v7, v70, v140
	v_exp_f32_e32 v7, v7
	v_sub_f32_e32 v8, v71, v140
	v_add_f32_e32 v2, v3, v2
	v_cvt_pk_bf16_f32 v171, v9, v10
	v_exp_f32_e32 v8, v8
	v_sub_f32_e32 v9, v72, v140
	v_add_f32_e32 v2, v4, v2
	v_exp_f32_e32 v9, v9
	v_sub_f32_e32 v10, v73, v140
	v_add_f32_e32 v2, v5, v2
	v_cvt_pk_bf16_f32 v164, v11, v12
	v_exp_f32_e32 v10, v10
	v_sub_f32_e32 v11, v74, v140
	v_add_f32_e32 v2, v6, v2
	v_exp_f32_e32 v11, v11
	v_sub_f32_e32 v12, v75, v140
	v_add_f32_e32 v2, v7, v2
	v_cvt_pk_bf16_f32 v165, v13, v14
	v_exp_f32_e32 v12, v12
	v_sub_f32_e32 v13, v76, v140
	v_add_f32_e32 v2, v8, v2
	v_exp_f32_e32 v13, v13
	v_sub_f32_e32 v14, v77, v140
	v_add_f32_e32 v2, v9, v2
	v_cvt_pk_bf16_f32 v166, v15, v16
	v_exp_f32_e32 v14, v14
	v_sub_f32_e32 v15, v78, v140
	v_add_f32_e32 v2, v10, v2
	v_exp_f32_e32 v15, v15
	v_sub_f32_e32 v16, v79, v140
	v_add_f32_e32 v2, v11, v2
	v_cvt_pk_bf16_f32 v167, v17, v18
	v_exp_f32_e32 v16, v16
	v_sub_f32_e32 v17, v80, v140
	v_add_f32_e32 v2, v12, v2
	v_exp_f32_e32 v17, v17
	v_sub_f32_e32 v18, v81, v140
	v_add_f32_e32 v2, v13, v2
	v_exp_f32_e32 v18, v18
	v_cvt_pk_bf16_f32 v160, v3, v4
	v_add_f32_e32 v2, v14, v2
	v_sub_f32_e32 v3, v82, v140
	v_add_f32_e32 v2, v15, v2
	v_exp_f32_e32 v3, v3
	v_sub_f32_e32 v4, v83, v140
	v_cvt_pk_bf16_f32 v161, v5, v6
	v_add_f32_e32 v2, v16, v2
	v_exp_f32_e32 v4, v4
	v_sub_f32_e32 v5, v84, v140
	v_add_f32_e32 v2, v17, v2
	v_exp_f32_e32 v5, v5
	v_sub_f32_e32 v6, v85, v140
	v_cvt_pk_bf16_f32 v162, v7, v8
	v_add_f32_e32 v2, v18, v2
	v_exp_f32_e32 v6, v6
	v_sub_f32_e32 v7, v86, v140
	v_exp_f32_e32 v7, v7
	v_sub_f32_e32 v8, v87, v140
	v_add_f32_e32 v2, v3, v2
	v_cvt_pk_bf16_f32 v163, v9, v10
	v_exp_f32_e32 v8, v8
	v_sub_f32_e32 v9, v88, v140
	v_add_f32_e32 v2, v4, v2
	v_exp_f32_e32 v9, v9
	v_sub_f32_e32 v10, v89, v140
	v_add_f32_e32 v2, v5, v2
	v_cvt_pk_bf16_f32 v156, v11, v12
	v_exp_f32_e32 v10, v10
	v_sub_f32_e32 v11, v90, v140
	v_add_f32_e32 v2, v6, v2
	v_exp_f32_e32 v11, v11
	v_sub_f32_e32 v12, v91, v140
	v_add_f32_e32 v2, v7, v2
	v_cvt_pk_bf16_f32 v157, v13, v14
	v_exp_f32_e32 v12, v12
	v_sub_f32_e32 v13, v92, v140
	v_add_f32_e32 v2, v8, v2
	v_exp_f32_e32 v13, v13
	v_sub_f32_e32 v14, v93, v140
	v_add_f32_e32 v2, v9, v2
	v_cvt_pk_bf16_f32 v158, v15, v16
	v_exp_f32_e32 v14, v14
	v_sub_f32_e32 v15, v94, v140
	v_add_f32_e32 v2, v10, v2
	v_exp_f32_e32 v15, v15
	v_sub_f32_e32 v16, v95, v140
	v_add_f32_e32 v2, v11, v2
	v_cvt_pk_bf16_f32 v159, v17, v18
	v_exp_f32_e32 v16, v16
	v_sub_f32_e32 v17, v96, v140
	v_add_f32_e32 v2, v12, v2
	v_exp_f32_e32 v17, v17
	v_sub_f32_e32 v18, v97, v140
	v_add_f32_e32 v2, v13, v2
	v_exp_f32_e32 v18, v18
	v_cvt_pk_bf16_f32 v152, v3, v4
	v_add_f32_e32 v2, v14, v2
	v_sub_f32_e32 v3, v98, v140
	v_add_f32_e32 v2, v15, v2
	v_exp_f32_e32 v3, v3
	v_sub_f32_e32 v4, v99, v140
	v_cvt_pk_bf16_f32 v153, v5, v6
	v_add_f32_e32 v2, v16, v2
	v_exp_f32_e32 v4, v4
	v_sub_f32_e32 v5, v100, v140
	v_add_f32_e32 v2, v17, v2
	v_exp_f32_e32 v5, v5
	v_sub_f32_e32 v6, v101, v140
	v_cvt_pk_bf16_f32 v154, v7, v8
	v_add_f32_e32 v2, v18, v2
	v_exp_f32_e32 v6, v6
	v_sub_f32_e32 v7, v102, v140
	v_exp_f32_e32 v7, v7
	v_sub_f32_e32 v8, v103, v140
	v_add_f32_e32 v2, v3, v2
	v_cvt_pk_bf16_f32 v155, v9, v10
	v_exp_f32_e32 v8, v8
	v_sub_f32_e32 v9, v104, v140
	v_add_f32_e32 v2, v4, v2
	v_exp_f32_e32 v9, v9
	v_sub_f32_e32 v10, v105, v140
	v_add_f32_e32 v2, v5, v2
	v_cvt_pk_bf16_f32 v148, v11, v12
	v_exp_f32_e32 v10, v10
	v_sub_f32_e32 v11, v106, v140
	v_add_f32_e32 v2, v6, v2
	v_exp_f32_e32 v11, v11
	v_sub_f32_e32 v12, v107, v140
	v_add_f32_e32 v2, v7, v2
	v_cvt_pk_bf16_f32 v149, v13, v14
	v_exp_f32_e32 v12, v12
	v_sub_f32_e32 v13, v108, v140
	v_add_f32_e32 v2, v8, v2
	v_exp_f32_e32 v13, v13
	v_sub_f32_e32 v14, v109, v140
	v_add_f32_e32 v2, v9, v2
	v_cvt_pk_bf16_f32 v150, v15, v16
	v_exp_f32_e32 v14, v14
	v_sub_f32_e32 v15, v110, v140
	v_add_f32_e32 v2, v10, v2
	v_exp_f32_e32 v15, v15
	v_sub_f32_e32 v16, v111, v140
	v_add_f32_e32 v2, v11, v2
	v_cvt_pk_bf16_f32 v151, v17, v18
	v_exp_f32_e32 v16, v16
	v_sub_f32_e32 v17, v112, v140
	v_add_f32_e32 v2, v12, v2
	v_exp_f32_e32 v17, v17
	v_sub_f32_e32 v18, v113, v140
	v_add_f32_e32 v2, v13, v2
	v_exp_f32_e32 v18, v18
	v_cvt_pk_bf16_f32 v136, v3, v4
	v_add_f32_e32 v2, v14, v2
	v_sub_f32_e32 v3, v114, v140
	v_add_f32_e32 v2, v15, v2
	v_exp_f32_e32 v3, v3
	v_sub_f32_e32 v4, v115, v140
	v_cvt_pk_bf16_f32 v137, v5, v6
	v_add_f32_e32 v2, v16, v2
	v_exp_f32_e32 v4, v4
	v_sub_f32_e32 v5, v116, v140
	v_add_f32_e32 v2, v17, v2
	v_exp_f32_e32 v5, v5
	v_sub_f32_e32 v6, v117, v140
	v_cvt_pk_bf16_f32 v138, v7, v8
	v_add_f32_e32 v2, v18, v2
	v_exp_f32_e32 v6, v6
	v_sub_f32_e32 v7, v118, v140
	v_exp_f32_e32 v7, v7
	v_sub_f32_e32 v8, v119, v140
	v_add_f32_e32 v2, v3, v2
	v_cvt_pk_bf16_f32 v139, v9, v10
	v_exp_f32_e32 v8, v8
	v_sub_f32_e32 v9, v120, v140
	v_add_f32_e32 v2, v4, v2
	v_exp_f32_e32 v9, v9
	v_sub_f32_e32 v10, v121, v140
	v_add_f32_e32 v2, v5, v2
	v_cvt_pk_bf16_f32 v132, v11, v12
	v_exp_f32_e32 v10, v10
	v_sub_f32_e32 v11, v122, v140
	v_add_f32_e32 v2, v6, v2
	v_exp_f32_e32 v11, v11
	v_sub_f32_e32 v12, v123, v140
	v_add_f32_e32 v2, v7, v2
	v_cvt_pk_bf16_f32 v133, v13, v14
	v_exp_f32_e32 v12, v12
	v_sub_f32_e32 v13, v124, v140
	v_add_f32_e32 v2, v8, v2
	v_exp_f32_e32 v13, v13
	v_sub_f32_e32 v14, v125, v140
	v_add_f32_e32 v2, v9, v2
	v_cvt_pk_bf16_f32 v134, v15, v16
	v_exp_f32_e32 v14, v14
	v_sub_f32_e32 v15, v126, v140
	v_add_f32_e32 v2, v10, v2
	v_exp_f32_e32 v15, v15
	v_sub_f32_e32 v16, v127, v140
	v_add_f32_e32 v2, v11, v2
	v_cvt_pk_bf16_f32 v135, v17, v18
	v_exp_f32_e32 v16, v16
	v_sub_f32_e32 v17, v128, v140
	v_add_f32_e32 v2, v12, v2
	v_exp_f32_e32 v17, v17
	v_sub_f32_e32 v18, v129, v140
	v_add_f32_e32 v2, v13, v2
	v_exp_f32_e32 v18, v18
	v_add_f32_e32 v2, v14, v2
	v_add_f32_e32 v2, v15, v2
	v_add_f32_e32 v2, v16, v2
	v_add_f32_e32 v2, v17, v2
	v_add_f32_e32 v217, v18, v2
	s_barrier
; #define LAS __attribute__((address_space(3)))
; __device__ __forceinline__ void attn_wg_unit(const Args& args, int l, int u, LAS unsigned char* lds, int tid_in) {
;     ...
;     sum += __shfl_xor(sum, 32);
;     const float inv = __builtin_amdgcn_rcpf(sum);
;     f32x16 ot[8];
; #pragma unroll
;     for (int dt = 0; dt < 8; ++dt)
; #pragma unroll
;         for (int i = 0; i < 16; ++i) ot[dt][i] = 0.f;
; #pragma unroll
;     for (int kt = 0; kt < 8; ++kt) {
;         if (kt < 7) { s0 = *(const u32x4*)(vsrc + 32 * (kt + 1)); s1 = *(const u32x4*)(vsrc + 32 * (kt + 1) + 8); }
;         const LAS unsigned char* cb = buf + (kt & 1) * 16384 + lane * 16;
; #pragma unroll
;         for (int dt = 0; dt < 8; ++dt)
; #pragma unroll
;             for (int s = 0; s < 2; ++s) { const bf16x8 vf = *(const LAS bf16x8*)(cb + (dt * 2 + s) * 1024); ot[dt] = __builtin_amdgcn_mfma_f32_32x32x16_bf16(vf, pf[kt][s], ot[dt], 0, 0, 0); }
;         if (kt < 7) {
;             LAS unsigned char* nb = buf + ((kt + 1) & 1) * 16384;
;             *(LAS u32x4*)(nb + vdst) = (u32x4){s0.x, s0.y, s1.x, s1.y}; *(LAS u32x4*)(nb + vdst + 512) = (u32x4){s0.z, s0.w, s1.z, s1.w};
;         }
;         __syncthreads();
;     }
	v_cvt_pk_bf16_f32 v140, v3, v4
	v_cvt_pk_bf16_f32 v141, v5, v6
	ds_bpermute_b32 v218, v196, v217
	global_load_dwordx4 v[196:199], v[214:215], off offset:80
	global_load_dwordx4 v[200:203], v[214:215], off offset:64
	ds_read_b128 v[2:5], v211 offset:8192
	v_cvt_pk_bf16_f32 v147, v17, v18
	ds_read_b128 v[18:21], v211 offset:9216
	v_cvt_pk_bf16_f32 v142, v7, v8
	v_cvt_pk_bf16_f32 v143, v9, v10
	v_cvt_pk_bf16_f32 v144, v11, v12
	v_cvt_pk_bf16_f32 v145, v13, v14
	v_cvt_pk_bf16_f32 v146, v15, v16
	s_waitcnt lgkmcnt(1)
	v_mfma_f32_32x32x16_bf16 v[2:17], v[2:5], v[192:195], 0
	ds_read_b128 v[66:69], v211 offset:15360
	ds_read_b128 v[82:85], v211 offset:17408
	ds_read_b128 v[114:117], v211 offset:21504
	s_waitcnt lgkmcnt(3)
	v_mfma_f32_32x32x16_bf16 v[2:17], v[18:21], v[188:191], v[2:17]
	ds_read_b128 v[18:21], v211 offset:10240
	s_waitcnt lgkmcnt(0)
	v_mfma_f32_32x32x16_bf16 v[50:65], v[18:21], v[192:195], 0
	ds_read_b128 v[18:21], v211 offset:11264
	s_waitcnt lgkmcnt(0)
	v_mfma_f32_32x32x16_bf16 v[50:65], v[18:21], v[188:191], v[50:65]
	ds_read_b128 v[18:21], v211 offset:12288
	s_waitcnt lgkmcnt(0)
	v_mfma_f32_32x32x16_bf16 v[34:49], v[18:21], v[192:195], 0
	ds_read_b128 v[18:21], v211 offset:13312
	s_waitcnt lgkmcnt(0)
	v_mfma_f32_32x32x16_bf16 v[34:49], v[18:21], v[188:191], v[34:49]
	ds_read_b128 v[18:21], v211 offset:14336
	s_waitcnt lgkmcnt(0)
	v_mfma_f32_32x32x16_bf16 v[18:33], v[18:21], v[192:195], 0
	v_mfma_f32_32x32x16_bf16 v[18:33], v[66:69], v[188:191], v[18:33]
	ds_read_b128 v[66:69], v211 offset:16384
	s_waitcnt lgkmcnt(0)
	v_mfma_f32_32x32x16_bf16 v[66:81], v[66:69], v[192:195], 0
	v_mfma_f32_32x32x16_bf16 v[66:81], v[82:85], v[188:191], v[66:81]
	ds_read_b128 v[82:85], v211 offset:18432
	s_waitcnt lgkmcnt(0)
	v_mfma_f32_32x32x16_bf16 v[98:113], v[82:85], v[192:195], 0
	ds_read_b128 v[82:85], v211 offset:19456
	s_waitcnt lgkmcnt(0)
	v_mfma_f32_32x32x16_bf16 v[98:113], v[82:85], v[188:191], v[98:113]
	ds_read_b128 v[82:85], v211 offset:20480
	s_waitcnt lgkmcnt(0)
	v_mfma_f32_32x32x16_bf16 v[82:97], v[82:85], v[192:195], 0
	v_mfma_f32_32x32x16_bf16 v[82:97], v[114:117], v[188:191], v[82:97]
	ds_read_b128 v[114:117], v211 offset:22528
	s_waitcnt lgkmcnt(0)
	v_mfma_f32_32x32x16_bf16 v[114:129], v[114:117], v[192:195], 0
	ds_read_b128 v[192:195], v211 offset:23552
	s_waitcnt lgkmcnt(0)
	v_mfma_f32_32x32x16_bf16 v[114:129], v[192:195], v[188:191], v[114:129]
	s_waitcnt vmcnt(0)
	v_mov_b32_e32 v188, v202
	v_mov_b32_e32 v189, v203
	v_mov_b32_e32 v190, v198
	v_mov_b32_e32 v191, v199
	v_mov_b32_e32 v202, v196
	v_mov_b32_e32 v203, v197
	ds_write_b128 v216, v[200:203] offset:24576
	ds_write_b128 v216, v[188:191] offset:25088
	s_waitcnt lgkmcnt(0)
	s_barrier
	global_load_dwordx4 v[188:191], v[214:215], off offset:144
	global_load_dwordx4 v[192:195], v[214:215], off offset:128
	ds_read_b128 v[196:199], v211 offset:24576
	ds_read_b128 v[200:203], v211 offset:25600
	s_waitcnt lgkmcnt(1)
	v_mfma_f32_32x32x16_bf16 v[2:17], v[196:199], v[184:187], v[2:17]
	ds_read_b128 v[196:199], v211 offset:26624
	s_waitcnt lgkmcnt(1)
	v_mfma_f32_32x32x16_bf16 v[2:17], v[200:203], v[180:183], v[2:17]
	ds_read_b128 v[200:203], v211 offset:27648
	s_waitcnt lgkmcnt(1)
	v_mfma_f32_32x32x16_bf16 v[50:65], v[196:199], v[184:187], v[50:65]
	ds_read_b128 v[196:199], v211 offset:28672
	s_waitcnt lgkmcnt(1)
	v_mfma_f32_32x32x16_bf16 v[50:65], v[200:203], v[180:183], v[50:65]
	ds_read_b128 v[200:203], v211 offset:29696
	s_waitcnt lgkmcnt(1)
	v_mfma_f32_32x32x16_bf16 v[34:49], v[196:199], v[184:187], v[34:49]
	ds_read_b128 v[196:199], v211 offset:30720
	s_waitcnt lgkmcnt(1)
	v_mfma_f32_32x32x16_bf16 v[34:49], v[200:203], v[180:183], v[34:49]
	ds_read_b128 v[200:203], v211 offset:31744
	s_waitcnt lgkmcnt(1)
	v_mfma_f32_32x32x16_bf16 v[18:33], v[196:199], v[184:187], v[18:33]
	ds_read_b128 v[196:199], v211 offset:32768
	s_waitcnt lgkmcnt(1)
	v_mfma_f32_32x32x16_bf16 v[18:33], v[200:203], v[180:183], v[18:33]
	ds_read_b128 v[200:203], v211 offset:33792
	s_waitcnt lgkmcnt(1)
	v_mfma_f32_32x32x16_bf16 v[66:81], v[196:199], v[184:187], v[66:81]
	ds_read_b128 v[196:199], v211 offset:34816
	s_waitcnt lgkmcnt(1)
	v_mfma_f32_32x32x16_bf16 v[66:81], v[200:203], v[180:183], v[66:81]
	ds_read_b128 v[200:203], v211 offset:35840
	s_waitcnt lgkmcnt(1)
	v_mfma_f32_32x32x16_bf16 v[98:113], v[196:199], v[184:187], v[98:113]
	ds_read_b128 v[196:199], v211 offset:36864
	s_waitcnt lgkmcnt(1)
	v_mfma_f32_32x32x16_bf16 v[98:113], v[200:203], v[180:183], v[98:113]
	ds_read_b128 v[200:203], v211 offset:37888
	s_waitcnt lgkmcnt(1)
	v_mfma_f32_32x32x16_bf16 v[82:97], v[196:199], v[184:187], v[82:97]
	ds_read_b128 v[196:199], v211 offset:38912
	s_waitcnt lgkmcnt(1)
	v_mfma_f32_32x32x16_bf16 v[82:97], v[200:203], v[180:183], v[82:97]
	ds_read_b128 v[200:203], v211 offset:39936
	s_waitcnt lgkmcnt(1)
	v_mfma_f32_32x32x16_bf16 v[114:129], v[196:199], v[184:187], v[114:129]
	s_waitcnt lgkmcnt(0)
	v_mfma_f32_32x32x16_bf16 v[114:129], v[200:203], v[180:183], v[114:129]
	s_waitcnt vmcnt(0)
	v_mov_b32_e32 v180, v194
	v_mov_b32_e32 v181, v195
	v_mov_b32_e32 v182, v190
	v_mov_b32_e32 v183, v191
	v_mov_b32_e32 v194, v188
	v_mov_b32_e32 v195, v189
	ds_write_b128 v216, v[192:195] offset:8192
	ds_write_b128 v216, v[180:183] offset:8704
	s_waitcnt lgkmcnt(0)
	s_barrier
; #define LAS __attribute__((address_space(3)))
; __device__ __forceinline__ void attn_wg_unit(const Args& args, int l, int u, LAS unsigned char* lds, int tid_in) {
;     ...
; #pragma unroll
;     for (int kt = 0; kt < 8; ++kt) {
;         if (kt < 7) { s0 = *(const u32x4*)(vsrc + 32 * (kt + 1)); s1 = *(const u32x4*)(vsrc + 32 * (kt + 1) + 8); }
;         const LAS unsigned char* cb = buf + (kt & 1) * 16384 + lane * 16;
; #pragma unroll
;         for (int dt = 0; dt < 8; ++dt)
; #pragma unroll
;             for (int s = 0; s < 2; ++s) { const bf16x8 vf = *(const LAS bf16x8*)(cb + (dt * 2 + s) * 1024); ot[dt] = __builtin_amdgcn_mfma_f32_32x32x16_bf16(vf, pf[kt][s], ot[dt], 0, 0, 0); }
;         if (kt < 7) {
;             LAS unsigned char* nb = buf + ((kt + 1) & 1) * 16384;
;             *(LAS u32x4*)(nb + vdst) = (u32x4){s0.x, s0.y, s1.x, s1.y}; *(LAS u32x4*)(nb + vdst + 512) = (u32x4){s0.z, s0.w, s1.z, s1.w};
;         }
;         __syncthreads();
;     }
	global_load_dwordx4 v[180:183], v[214:215], off offset:208
	global_load_dwordx4 v[184:187], v[214:215], off offset:192
	ds_read_b128 v[188:191], v211 offset:8192
	ds_read_b128 v[192:195], v211 offset:9216
	ds_read_b128 v[196:199], v211 offset:10240
	ds_read_b128 v[200:203], v211 offset:11264
	s_waitcnt lgkmcnt(3)
	v_mfma_f32_32x32x16_bf16 v[2:17], v[188:191], v[176:179], v[2:17]
	ds_read_b128 v[188:191], v211 offset:12288
	s_waitcnt lgkmcnt(3)
	v_mfma_f32_32x32x16_bf16 v[2:17], v[192:195], v[172:175], v[2:17]
	ds_read_b128 v[192:195], v211 offset:13312
	s_waitcnt lgkmcnt(3)
	v_mfma_f32_32x32x16_bf16 v[50:65], v[196:199], v[176:179], v[50:65]
	ds_read_b128 v[196:199], v211 offset:14336
	s_waitcnt lgkmcnt(3)
	v_mfma_f32_32x32x16_bf16 v[50:65], v[200:203], v[172:175], v[50:65]
	ds_read_b128 v[200:203], v211 offset:15360
	s_waitcnt lgkmcnt(3)
	v_mfma_f32_32x32x16_bf16 v[34:49], v[188:191], v[176:179], v[34:49]
	ds_read_b128 v[188:191], v211 offset:16384
	s_waitcnt lgkmcnt(3)
	v_mfma_f32_32x32x16_bf16 v[34:49], v[192:195], v[172:175], v[34:49]
	ds_read_b128 v[192:195], v211 offset:17408
	s_waitcnt lgkmcnt(3)
	v_mfma_f32_32x32x16_bf16 v[18:33], v[196:199], v[176:179], v[18:33]
	ds_read_b128 v[196:199], v211 offset:18432
	s_waitcnt lgkmcnt(3)
	v_mfma_f32_32x32x16_bf16 v[18:33], v[200:203], v[172:175], v[18:33]
	ds_read_b128 v[200:203], v211 offset:19456
	s_waitcnt lgkmcnt(3)
	v_mfma_f32_32x32x16_bf16 v[66:81], v[188:191], v[176:179], v[66:81]
	ds_read_b128 v[188:191], v211 offset:20480
	s_waitcnt lgkmcnt(3)
	v_mfma_f32_32x32x16_bf16 v[66:81], v[192:195], v[172:175], v[66:81]
	ds_read_b128 v[192:195], v211 offset:21504
	s_waitcnt lgkmcnt(3)
	v_mfma_f32_32x32x16_bf16 v[98:113], v[196:199], v[176:179], v[98:113]
	ds_read_b128 v[196:199], v211 offset:22528
	s_waitcnt lgkmcnt(3)
	v_mfma_f32_32x32x16_bf16 v[98:113], v[200:203], v[172:175], v[98:113]
	ds_read_b128 v[200:203], v211 offset:23552
	s_waitcnt lgkmcnt(3)
	v_mfma_f32_32x32x16_bf16 v[82:97], v[188:191], v[176:179], v[82:97]
	s_waitcnt lgkmcnt(2)
	v_mfma_f32_32x32x16_bf16 v[82:97], v[192:195], v[172:175], v[82:97]
	s_waitcnt lgkmcnt(1)
	v_mfma_f32_32x32x16_bf16 v[114:129], v[196:199], v[176:179], v[114:129]
	s_waitcnt lgkmcnt(0)
	v_mfma_f32_32x32x16_bf16 v[114:129], v[200:203], v[172:175], v[114:129]
	s_waitcnt vmcnt(0)
	v_mov_b32_e32 v172, v186
	v_mov_b32_e32 v173, v187
	v_mov_b32_e32 v174, v182
	v_mov_b32_e32 v175, v183
	v_mov_b32_e32 v186, v180
	v_mov_b32_e32 v187, v181
	ds_write_b128 v216, v[184:187] offset:24576
	ds_write_b128 v216, v[172:175] offset:25088
	s_waitcnt lgkmcnt(0)
	s_barrier
	global_load_dwordx4 v[172:175], v[214:215], off offset:272
	global_load_dwordx4 v[176:179], v[214:215], off offset:256
	ds_read_b128 v[180:183], v211 offset:24576
	ds_read_b128 v[184:187], v211 offset:25600
	ds_read_b128 v[188:191], v211 offset:26624
	ds_read_b128 v[192:195], v211 offset:27648
	ds_read_b128 v[196:199], v211 offset:28672
	ds_read_b128 v[200:203], v211 offset:29696
	s_waitcnt lgkmcnt(5)
	v_mfma_f32_32x32x16_bf16 v[2:17], v[180:183], v[168:171], v[2:17]
	ds_read_b128 v[180:183], v211 offset:30720
	s_waitcnt lgkmcnt(5)
	v_mfma_f32_32x32x16_bf16 v[2:17], v[184:187], v[164:167], v[2:17]
	ds_read_b128 v[184:187], v211 offset:31744
	s_waitcnt lgkmcnt(5)
	v_mfma_f32_32x32x16_bf16 v[50:65], v[188:191], v[168:171], v[50:65]
	ds_read_b128 v[188:191], v211 offset:32768
	s_waitcnt lgkmcnt(5)
	v_mfma_f32_32x32x16_bf16 v[50:65], v[192:195], v[164:167], v[50:65]
	ds_read_b128 v[192:195], v211 offset:33792
	s_waitcnt lgkmcnt(5)
	v_mfma_f32_32x32x16_bf16 v[34:49], v[196:199], v[168:171], v[34:49]
	ds_read_b128 v[196:199], v211 offset:34816
	s_waitcnt lgkmcnt(5)
	v_mfma_f32_32x32x16_bf16 v[34:49], v[200:203], v[164:167], v[34:49]
	ds_read_b128 v[200:203], v211 offset:35840
	s_waitcnt lgkmcnt(5)
	v_mfma_f32_32x32x16_bf16 v[18:33], v[180:183], v[168:171], v[18:33]
	ds_read_b128 v[180:183], v211 offset:36864
	s_waitcnt lgkmcnt(5)
	v_mfma_f32_32x32x16_bf16 v[18:33], v[184:187], v[164:167], v[18:33]
	ds_read_b128 v[184:187], v211 offset:37888
	s_waitcnt lgkmcnt(5)
	v_mfma_f32_32x32x16_bf16 v[66:81], v[188:191], v[168:171], v[66:81]
	ds_read_b128 v[188:191], v211 offset:38912
	s_waitcnt lgkmcnt(5)
	v_mfma_f32_32x32x16_bf16 v[66:81], v[192:195], v[164:167], v[66:81]
	ds_read_b128 v[192:195], v211 offset:39936
	s_waitcnt lgkmcnt(5)
	v_mfma_f32_32x32x16_bf16 v[98:113], v[196:199], v[168:171], v[98:113]
	s_waitcnt lgkmcnt(4)
	v_mfma_f32_32x32x16_bf16 v[98:113], v[200:203], v[164:167], v[98:113]
	s_waitcnt lgkmcnt(3)
	v_mfma_f32_32x32x16_bf16 v[82:97], v[180:183], v[168:171], v[82:97]
	s_waitcnt lgkmcnt(2)
	v_mfma_f32_32x32x16_bf16 v[82:97], v[184:187], v[164:167], v[82:97]
	s_waitcnt lgkmcnt(1)
	v_mfma_f32_32x32x16_bf16 v[114:129], v[188:191], v[168:171], v[114:129]
	s_waitcnt lgkmcnt(0)
	v_mfma_f32_32x32x16_bf16 v[114:129], v[192:195], v[164:167], v[114:129]
	s_waitcnt vmcnt(0)
	v_mov_b32_e32 v164, v178
	v_mov_b32_e32 v165, v179
	v_mov_b32_e32 v166, v174
	v_mov_b32_e32 v167, v175
	v_mov_b32_e32 v178, v172
	v_mov_b32_e32 v179, v173
	ds_write_b128 v216, v[176:179] offset:8192
	ds_write_b128 v216, v[164:167] offset:8704
	s_waitcnt lgkmcnt(0)
	s_barrier
; #define LAS __attribute__((address_space(3)))
; __device__ __forceinline__ void attn_wg_unit(const Args& args, int l, int u, LAS unsigned char* lds, int tid_in) {
;     ...
; #pragma unroll
;     for (int kt = 0; kt < 8; ++kt) {
;         if (kt < 7) { s0 = *(const u32x4*)(vsrc + 32 * (kt + 1)); s1 = *(const u32x4*)(vsrc + 32 * (kt + 1) + 8); }
;         const LAS unsigned char* cb = buf + (kt & 1) * 16384 + lane * 16;
; #pragma unroll
;         for (int dt = 0; dt < 8; ++dt)
; #pragma unroll
;             for (int s = 0; s < 2; ++s) { const bf16x8 vf = *(const LAS bf16x8*)(cb + (dt * 2 + s) * 1024); ot[dt] = __builtin_amdgcn_mfma_f32_32x32x16_bf16(vf, pf[kt][s], ot[dt], 0, 0, 0); }
;         if (kt < 7) {
;             LAS unsigned char* nb = buf + ((kt + 1) & 1) * 16384;
;             *(LAS u32x4*)(nb + vdst) = (u32x4){s0.x, s0.y, s1.x, s1.y}; *(LAS u32x4*)(nb + vdst + 512) = (u32x4){s0.z, s0.w, s1.z, s1.w};
;         }
;         __syncthreads();
;     }
	global_load_dwordx4 v[164:167], v[214:215], off offset:336
	global_load_dwordx4 v[168:171], v[214:215], off offset:320
	ds_read_b128 v[172:175], v211 offset:8192
	ds_read_b128 v[176:179], v211 offset:9216
	ds_read_b128 v[180:183], v211 offset:10240
	ds_read_b128 v[184:187], v211 offset:11264
	ds_read_b128 v[188:191], v211 offset:12288
	ds_read_b128 v[192:195], v211 offset:13312
	s_waitcnt lgkmcnt(5)
	v_mfma_f32_32x32x16_bf16 v[2:17], v[172:175], v[160:163], v[2:17]
	ds_read_b128 v[196:199], v211 offset:14336
	s_waitcnt lgkmcnt(5)
	v_mfma_f32_32x32x16_bf16 v[2:17], v[176:179], v[156:159], v[2:17]
	ds_read_b128 v[200:203], v211 offset:15360
	s_waitcnt lgkmcnt(5)
	v_mfma_f32_32x32x16_bf16 v[50:65], v[180:183], v[160:163], v[50:65]
	ds_read_b128 v[172:175], v211 offset:16384
	s_waitcnt lgkmcnt(5)
	v_mfma_f32_32x32x16_bf16 v[50:65], v[184:187], v[156:159], v[50:65]
	ds_read_b128 v[176:179], v211 offset:17408
	s_waitcnt lgkmcnt(5)
	v_mfma_f32_32x32x16_bf16 v[34:49], v[188:191], v[160:163], v[34:49]
	ds_read_b128 v[180:183], v211 offset:18432
	s_waitcnt lgkmcnt(5)
	v_mfma_f32_32x32x16_bf16 v[34:49], v[192:195], v[156:159], v[34:49]
	ds_read_b128 v[184:187], v211 offset:19456
	s_waitcnt lgkmcnt(5)
	v_mfma_f32_32x32x16_bf16 v[18:33], v[196:199], v[160:163], v[18:33]
	ds_read_b128 v[188:191], v211 offset:20480
	s_waitcnt lgkmcnt(5)
	v_mfma_f32_32x32x16_bf16 v[18:33], v[200:203], v[156:159], v[18:33]
	ds_read_b128 v[192:195], v211 offset:21504
	s_waitcnt lgkmcnt(5)
	v_mfma_f32_32x32x16_bf16 v[66:81], v[172:175], v[160:163], v[66:81]
	ds_read_b128 v[196:199], v211 offset:22528
	s_waitcnt lgkmcnt(5)
	v_mfma_f32_32x32x16_bf16 v[66:81], v[176:179], v[156:159], v[66:81]
	ds_read_b128 v[200:203], v211 offset:23552
	s_waitcnt lgkmcnt(5)
	v_mfma_f32_32x32x16_bf16 v[98:113], v[180:183], v[160:163], v[98:113]
	s_waitcnt lgkmcnt(4)
	v_mfma_f32_32x32x16_bf16 v[98:113], v[184:187], v[156:159], v[98:113]
	s_waitcnt lgkmcnt(3)
	v_mfma_f32_32x32x16_bf16 v[82:97], v[188:191], v[160:163], v[82:97]
	s_waitcnt lgkmcnt(2)
	v_mfma_f32_32x32x16_bf16 v[82:97], v[192:195], v[156:159], v[82:97]
	s_waitcnt lgkmcnt(1)
	v_mfma_f32_32x32x16_bf16 v[114:129], v[196:199], v[160:163], v[114:129]
	s_waitcnt lgkmcnt(0)
	v_mfma_f32_32x32x16_bf16 v[114:129], v[200:203], v[156:159], v[114:129]
	s_waitcnt vmcnt(0)
	v_mov_b32_e32 v156, v170
	v_mov_b32_e32 v157, v171
	v_mov_b32_e32 v158, v166
	v_mov_b32_e32 v159, v167
	v_mov_b32_e32 v170, v164
	v_mov_b32_e32 v171, v165
	ds_write_b128 v216, v[168:171] offset:24576
	ds_write_b128 v216, v[156:159] offset:25088
	s_waitcnt lgkmcnt(0)
	s_barrier
	global_load_dwordx4 v[156:159], v[214:215], off offset:400
	global_load_dwordx4 v[160:163], v[214:215], off offset:384
	ds_read_b128 v[164:167], v211 offset:24576
	ds_read_b128 v[168:171], v211 offset:25600
	ds_read_b128 v[172:175], v211 offset:26624
	ds_read_b128 v[176:179], v211 offset:27648
	ds_read_b128 v[180:183], v211 offset:28672
	ds_read_b128 v[184:187], v211 offset:29696
	s_waitcnt lgkmcnt(5)
	v_mfma_f32_32x32x16_bf16 v[2:17], v[164:167], v[152:155], v[2:17]
	ds_read_b128 v[188:191], v211 offset:30720
	s_waitcnt lgkmcnt(5)
	v_mfma_f32_32x32x16_bf16 v[2:17], v[168:171], v[148:151], v[2:17]
	ds_read_b128 v[192:195], v211 offset:31744
	s_waitcnt lgkmcnt(5)
	v_mfma_f32_32x32x16_bf16 v[50:65], v[172:175], v[152:155], v[50:65]
	ds_read_b128 v[164:167], v211 offset:32768
	s_waitcnt lgkmcnt(5)
	v_mfma_f32_32x32x16_bf16 v[50:65], v[176:179], v[148:151], v[50:65]
	ds_read_b128 v[168:171], v211 offset:33792
	s_waitcnt lgkmcnt(5)
	v_mfma_f32_32x32x16_bf16 v[34:49], v[180:183], v[152:155], v[34:49]
	ds_read_b128 v[172:175], v211 offset:34816
	s_waitcnt lgkmcnt(5)
	v_mfma_f32_32x32x16_bf16 v[34:49], v[184:187], v[148:151], v[34:49]
	ds_read_b128 v[176:179], v211 offset:35840
	s_waitcnt lgkmcnt(5)
	v_mfma_f32_32x32x16_bf16 v[18:33], v[188:191], v[152:155], v[18:33]
	ds_read_b128 v[180:183], v211 offset:36864
	s_waitcnt lgkmcnt(5)
	v_mfma_f32_32x32x16_bf16 v[18:33], v[192:195], v[148:151], v[18:33]
	ds_read_b128 v[184:187], v211 offset:37888
	s_waitcnt lgkmcnt(5)
	v_mfma_f32_32x32x16_bf16 v[66:81], v[164:167], v[152:155], v[66:81]
	ds_read_b128 v[188:191], v211 offset:38912
	s_waitcnt lgkmcnt(5)
	v_mfma_f32_32x32x16_bf16 v[66:81], v[168:171], v[148:151], v[66:81]
	ds_read_b128 v[192:195], v211 offset:39936
	s_waitcnt lgkmcnt(5)
	v_mfma_f32_32x32x16_bf16 v[98:113], v[172:175], v[152:155], v[98:113]
	s_waitcnt lgkmcnt(4)
	v_mfma_f32_32x32x16_bf16 v[98:113], v[176:179], v[148:151], v[98:113]
	s_waitcnt lgkmcnt(3)
	v_mfma_f32_32x32x16_bf16 v[82:97], v[180:183], v[152:155], v[82:97]
	s_waitcnt lgkmcnt(2)
	v_mfma_f32_32x32x16_bf16 v[82:97], v[184:187], v[148:151], v[82:97]
	s_waitcnt lgkmcnt(1)
	v_mfma_f32_32x32x16_bf16 v[114:129], v[188:191], v[152:155], v[114:129]
	s_waitcnt lgkmcnt(0)
	v_mfma_f32_32x32x16_bf16 v[114:129], v[192:195], v[148:151], v[114:129]
	s_waitcnt vmcnt(0)
	v_mov_b32_e32 v148, v162
	v_mov_b32_e32 v149, v163
	v_mov_b32_e32 v150, v158
	v_mov_b32_e32 v151, v159
	v_mov_b32_e32 v162, v156
	v_mov_b32_e32 v163, v157
	ds_write_b128 v216, v[160:163] offset:8192
	ds_write_b128 v216, v[148:151] offset:8704
	s_waitcnt lgkmcnt(0)
	s_barrier
; #define LAS __attribute__((address_space(3)))
; __device__ __forceinline__ void attn_wg_unit(const Args& args, int l, int u, LAS unsigned char* lds, int tid_in) {
;     ...
; #pragma unroll
;     for (int kt = 0; kt < 8; ++kt) {
;         if (kt < 7) { s0 = *(const u32x4*)(vsrc + 32 * (kt + 1)); s1 = *(const u32x4*)(vsrc + 32 * (kt + 1) + 8); }
;         const LAS unsigned char* cb = buf + (kt & 1) * 16384 + lane * 16;
; #pragma unroll
;         for (int dt = 0; dt < 8; ++dt)
; #pragma unroll
;             for (int s = 0; s < 2; ++s) { const bf16x8 vf = *(const LAS bf16x8*)(cb + (dt * 2 + s) * 1024); ot[dt] = __builtin_amdgcn_mfma_f32_32x32x16_bf16(vf, pf[kt][s], ot[dt], 0, 0, 0); }
;         if (kt < 7) {
;             LAS unsigned char* nb = buf + ((kt + 1) & 1) * 16384;
;             *(LAS u32x4*)(nb + vdst) = (u32x4){s0.x, s0.y, s1.x, s1.y}; *(LAS u32x4*)(nb + vdst + 512) = (u32x4){s0.z, s0.w, s1.z, s1.w};
;         }
;         __syncthreads();
;     }
	global_load_dwordx4 v[148:151], v[214:215], off offset:464
	global_load_dwordx4 v[152:155], v[214:215], off offset:448
	ds_read_b128 v[156:159], v211 offset:8192
	ds_read_b128 v[160:163], v211 offset:9216
	ds_read_b128 v[164:167], v211 offset:10240
	ds_read_b128 v[168:171], v211 offset:11264
	ds_read_b128 v[172:175], v211 offset:12288
	ds_read_b128 v[176:179], v211 offset:13312
	s_waitcnt lgkmcnt(5)
	v_mfma_f32_32x32x16_bf16 v[2:17], v[156:159], v[136:139], v[2:17]
	ds_read_b128 v[180:183], v211 offset:14336
	s_waitcnt lgkmcnt(5)
	v_mfma_f32_32x32x16_bf16 v[2:17], v[160:163], v[132:135], v[2:17]
	ds_read_b128 v[184:187], v211 offset:15360
	s_waitcnt lgkmcnt(5)
	v_mfma_f32_32x32x16_bf16 v[50:65], v[164:167], v[136:139], v[50:65]
	ds_read_b128 v[156:159], v211 offset:16384
	s_waitcnt lgkmcnt(5)
	v_mfma_f32_32x32x16_bf16 v[50:65], v[168:171], v[132:135], v[50:65]
	ds_read_b128 v[160:163], v211 offset:17408
	s_waitcnt lgkmcnt(5)
	v_mfma_f32_32x32x16_bf16 v[34:49], v[172:175], v[136:139], v[34:49]
	ds_read_b128 v[164:167], v211 offset:18432
	s_waitcnt lgkmcnt(5)
	v_mfma_f32_32x32x16_bf16 v[34:49], v[176:179], v[132:135], v[34:49]
	ds_read_b128 v[168:171], v211 offset:19456
	s_waitcnt lgkmcnt(5)
	v_mfma_f32_32x32x16_bf16 v[18:33], v[180:183], v[136:139], v[18:33]
	ds_read_b128 v[172:175], v211 offset:20480
	s_waitcnt lgkmcnt(5)
	v_mfma_f32_32x32x16_bf16 v[18:33], v[184:187], v[132:135], v[18:33]
	ds_read_b128 v[176:179], v211 offset:21504
	s_waitcnt lgkmcnt(5)
	v_mfma_f32_32x32x16_bf16 v[66:81], v[156:159], v[136:139], v[66:81]
	ds_read_b128 v[180:183], v211 offset:22528
	s_waitcnt lgkmcnt(5)
	v_mfma_f32_32x32x16_bf16 v[66:81], v[160:163], v[132:135], v[66:81]
	ds_read_b128 v[184:187], v211 offset:23552
	s_waitcnt lgkmcnt(5)
	v_mfma_f32_32x32x16_bf16 v[98:113], v[164:167], v[136:139], v[98:113]
	s_waitcnt lgkmcnt(4)
	v_mfma_f32_32x32x16_bf16 v[98:113], v[168:171], v[132:135], v[98:113]
	s_waitcnt lgkmcnt(3)
	v_mfma_f32_32x32x16_bf16 v[82:97], v[172:175], v[136:139], v[82:97]
	s_waitcnt lgkmcnt(2)
	v_mfma_f32_32x32x16_bf16 v[82:97], v[176:179], v[132:135], v[82:97]
	s_waitcnt lgkmcnt(1)
	v_mfma_f32_32x32x16_bf16 v[114:129], v[180:183], v[136:139], v[114:129]
	s_waitcnt lgkmcnt(0)
	v_mfma_f32_32x32x16_bf16 v[114:129], v[184:187], v[132:135], v[114:129]
	s_waitcnt vmcnt(0)
	v_mov_b32_e32 v132, v154
	v_mov_b32_e32 v133, v155
	v_mov_b32_e32 v134, v150
	v_mov_b32_e32 v135, v151
	v_mov_b32_e32 v154, v148
	v_mov_b32_e32 v155, v149
	ds_write_b128 v216, v[152:155] offset:24576
	ds_write_b128 v216, v[132:135] offset:25088
	s_waitcnt lgkmcnt(0)
	s_barrier
	ds_read_b128 v[132:135], v211 offset:24576
	ds_read_b128 v[136:139], v211 offset:25600
	ds_read_b128 v[148:151], v211 offset:26624
	ds_read_b128 v[152:155], v211 offset:27648
	ds_read_b128 v[156:159], v211 offset:28672
	ds_read_b128 v[160:163], v211 offset:29696
	s_waitcnt lgkmcnt(5)
	v_mfma_f32_32x32x16_bf16 v[2:17], v[132:135], v[140:143], v[2:17]
	ds_read_b128 v[164:167], v211 offset:30720
	s_waitcnt lgkmcnt(5)
	v_mfma_f32_32x32x16_bf16 v[2:17], v[136:139], v[144:147], v[2:17]
	ds_read_b128 v[168:171], v211 offset:31744
	s_waitcnt lgkmcnt(5)
	v_mfma_f32_32x32x16_bf16 v[50:65], v[148:151], v[140:143], v[50:65]
	ds_read_b128 v[132:135], v211 offset:32768
	s_waitcnt lgkmcnt(5)
	v_mfma_f32_32x32x16_bf16 v[50:65], v[152:155], v[144:147], v[50:65]
	ds_read_b128 v[136:139], v211 offset:33792
	s_waitcnt lgkmcnt(5)
	v_mfma_f32_32x32x16_bf16 v[34:49], v[156:159], v[140:143], v[34:49]
	ds_read_b128 v[148:151], v211 offset:34816
	s_waitcnt lgkmcnt(5)
	v_mfma_f32_32x32x16_bf16 v[34:49], v[160:163], v[144:147], v[34:49]
	ds_read_b128 v[152:155], v211 offset:35840
	s_waitcnt lgkmcnt(5)
	v_mfma_f32_32x32x16_bf16 v[18:33], v[164:167], v[140:143], v[18:33]
	ds_read_b128 v[156:159], v211 offset:36864
	s_waitcnt lgkmcnt(5)
	v_mfma_f32_32x32x16_bf16 v[18:33], v[168:171], v[144:147], v[18:33]
	ds_read_b128 v[160:163], v211 offset:37888
	s_waitcnt lgkmcnt(5)
	v_mfma_f32_32x32x16_bf16 v[66:81], v[132:135], v[140:143], v[66:81]
	ds_read_b128 v[164:167], v211 offset:38912
	s_waitcnt lgkmcnt(5)
	v_mfma_f32_32x32x16_bf16 v[66:81], v[136:139], v[144:147], v[66:81]
	ds_read_b128 v[168:171], v211 offset:39936
	s_waitcnt lgkmcnt(5)
	v_mfma_f32_32x32x16_bf16 v[98:113], v[148:151], v[140:143], v[98:113]
	s_waitcnt lgkmcnt(4)
	v_mfma_f32_32x32x16_bf16 v[98:113], v[152:155], v[144:147], v[98:113]
	s_waitcnt lgkmcnt(3)
	v_mfma_f32_32x32x16_bf16 v[82:97], v[156:159], v[140:143], v[82:97]
	s_waitcnt lgkmcnt(2)
	v_mfma_f32_32x32x16_bf16 v[82:97], v[160:163], v[144:147], v[82:97]
	s_waitcnt lgkmcnt(1)
	v_mfma_f32_32x32x16_bf16 v[114:129], v[164:167], v[140:143], v[114:129]
	s_waitcnt lgkmcnt(0)
	s_barrier
; __device__ __forceinline__ unsigned cvtpk(float lo, float hi) { f32x2 v = {lo, hi}; bf16x2_t b = __builtin_convertvector(v, bf16x2_t); return __builtin_bit_cast(unsigned, b); }
; __device__ __forceinline__ void attn_wg_unit(const Args& args, int l, int u, LAS unsigned char* lds, int tid_in) {
;     ...
;     sum += __shfl_xor(sum, 32);
;     const float inv = __builtin_amdgcn_rcpf(sum);
;     ...
;     bf16_t* op = AMEM + (size_t)(row0 + r32) * MW + head * MHD;
; #pragma unroll
;     for (int dt = 0; dt < 8; ++dt)
; #pragma unroll
;         for (int ig = 0; ig < 4; ++ig) {
;             u32x2 w; w.x = cvtpk(ot[dt][4 * ig] * inv, ot[dt][4 * ig + 1] * inv); w.y = cvtpk(ot[dt][4 * ig + 2] * inv, ot[dt][4 * ig + 3] * inv);
;             *(u32x2*)(op + 32 * dt + 8 * ig + 4 * hh) = w;
;         }
	v_mfma_f32_32x32x16_bf16 v[114:129], v[168:171], v[144:147], v[114:129]
	v_add_f32_e32 v132, v217, v218
	v_rcp_f32_e32 v132, v132
	v_lshlrev_b64 v[134:135], 11, v[212:213]
	v_lshl_add_u64 v[134:135], s[90:91], 0, v[134:135]
	v_lshl_add_u64 v[134:135], v[134:135], 0, s[80:81]
	v_pk_mul_f32 v[2:3], v[132:133], v[2:3] op_sel_hi:[0,1]
	v_pk_mul_f32 v[4:5], v[132:133], v[4:5] op_sel_hi:[0,1]
	v_lshl_add_u64 v[134:135], v[134:135], 0, v[130:131]
	v_cvt_pk_bf16_f32 v2, v2, v3
	v_cvt_pk_bf16_f32 v3, v4, v5
	global_store_dwordx2 v[134:135], v[2:3], off
	v_pk_mul_f32 v[2:3], v[132:133], v[6:7] op_sel_hi:[0,1]
	v_pk_mul_f32 v[4:5], v[132:133], v[8:9] op_sel_hi:[0,1]
	v_cvt_pk_bf16_f32 v2, v2, v3
	v_cvt_pk_bf16_f32 v3, v4, v5
	global_store_dwordx2 v[134:135], v[2:3], off offset:16
	v_pk_mul_f32 v[2:3], v[132:133], v[10:11] op_sel_hi:[0,1]
	v_pk_mul_f32 v[4:5], v[132:133], v[12:13] op_sel_hi:[0,1]
	v_cvt_pk_bf16_f32 v2, v2, v3
	v_cvt_pk_bf16_f32 v3, v4, v5
	global_store_dwordx2 v[134:135], v[2:3], off offset:32
	v_pk_mul_f32 v[2:3], v[132:133], v[14:15] op_sel_hi:[0,1]
	v_pk_mul_f32 v[4:5], v[132:133], v[16:17] op_sel_hi:[0,1]
	v_cvt_pk_bf16_f32 v2, v2, v3
	v_cvt_pk_bf16_f32 v3, v4, v5
	global_store_dwordx2 v[134:135], v[2:3], off offset:48
	v_pk_mul_f32 v[2:3], v[132:133], v[50:51] op_sel_hi:[0,1]
	v_pk_mul_f32 v[4:5], v[132:133], v[52:53] op_sel_hi:[0,1]
	v_cvt_pk_bf16_f32 v2, v2, v3
	v_cvt_pk_bf16_f32 v3, v4, v5
	global_store_dwordx2 v[134:135], v[2:3], off offset:64
	v_pk_mul_f32 v[2:3], v[132:133], v[54:55] op_sel_hi:[0,1]
	v_pk_mul_f32 v[4:5], v[132:133], v[56:57] op_sel_hi:[0,1]
	v_cvt_pk_bf16_f32 v2, v2, v3
	v_cvt_pk_bf16_f32 v3, v4, v5
	global_store_dwordx2 v[134:135], v[2:3], off offset:80
	v_pk_mul_f32 v[2:3], v[132:133], v[58:59] op_sel_hi:[0,1]
	v_pk_mul_f32 v[4:5], v[132:133], v[60:61] op_sel_hi:[0,1]
	v_cvt_pk_bf16_f32 v2, v2, v3
	v_cvt_pk_bf16_f32 v3, v4, v5
	global_store_dwordx2 v[134:135], v[2:3], off offset:96
	v_pk_mul_f32 v[2:3], v[132:133], v[62:63] op_sel_hi:[0,1]
	v_pk_mul_f32 v[4:5], v[132:133], v[64:65] op_sel_hi:[0,1]
	v_cvt_pk_bf16_f32 v2, v2, v3
	v_cvt_pk_bf16_f32 v3, v4, v5
	global_store_dwordx2 v[134:135], v[2:3], off offset:112
	v_pk_mul_f32 v[2:3], v[132:133], v[34:35] op_sel_hi:[0,1]
	v_pk_mul_f32 v[4:5], v[132:133], v[36:37] op_sel_hi:[0,1]
	v_cvt_pk_bf16_f32 v2, v2, v3
	v_cvt_pk_bf16_f32 v3, v4, v5
	global_store_dwordx2 v[134:135], v[2:3], off offset:128
	v_pk_mul_f32 v[2:3], v[132:133], v[38:39] op_sel_hi:[0,1]
	v_pk_mul_f32 v[4:5], v[132:133], v[40:41] op_sel_hi:[0,1]
	v_cvt_pk_bf16_f32 v2, v2, v3
	v_cvt_pk_bf16_f32 v3, v4, v5
	global_store_dwordx2 v[134:135], v[2:3], off offset:144
	v_pk_mul_f32 v[2:3], v[132:133], v[42:43] op_sel_hi:[0,1]
	v_pk_mul_f32 v[4:5], v[132:133], v[44:45] op_sel_hi:[0,1]
	v_cvt_pk_bf16_f32 v2, v2, v3
	v_cvt_pk_bf16_f32 v3, v4, v5
	global_store_dwordx2 v[134:135], v[2:3], off offset:160
	v_pk_mul_f32 v[2:3], v[132:133], v[46:47] op_sel_hi:[0,1]
	v_pk_mul_f32 v[4:5], v[132:133], v[48:49] op_sel_hi:[0,1]
	v_cvt_pk_bf16_f32 v2, v2, v3
	v_cvt_pk_bf16_f32 v3, v4, v5
	global_store_dwordx2 v[134:135], v[2:3], off offset:176
	v_pk_mul_f32 v[2:3], v[132:133], v[18:19] op_sel_hi:[0,1]
	v_pk_mul_f32 v[4:5], v[132:133], v[20:21] op_sel_hi:[0,1]
	v_cvt_pk_bf16_f32 v2, v2, v3
	v_cvt_pk_bf16_f32 v3, v4, v5
	global_store_dwordx2 v[134:135], v[2:3], off offset:192
	v_pk_mul_f32 v[2:3], v[132:133], v[22:23] op_sel_hi:[0,1]
	v_pk_mul_f32 v[4:5], v[132:133], v[24:25] op_sel_hi:[0,1]
	v_cvt_pk_bf16_f32 v2, v2, v3
	v_cvt_pk_bf16_f32 v3, v4, v5
	global_store_dwordx2 v[134:135], v[2:3], off offset:208
	v_pk_mul_f32 v[2:3], v[132:133], v[26:27] op_sel_hi:[0,1]
	v_pk_mul_f32 v[4:5], v[132:133], v[28:29] op_sel_hi:[0,1]
	v_cvt_pk_bf16_f32 v2, v2, v3
	v_cvt_pk_bf16_f32 v3, v4, v5
	global_store_dwordx2 v[134:135], v[2:3], off offset:224
	v_pk_mul_f32 v[2:3], v[132:133], v[30:31] op_sel_hi:[0,1]
	v_pk_mul_f32 v[4:5], v[132:133], v[32:33] op_sel_hi:[0,1]
; __device__ __forceinline__ unsigned cvtpk(float lo, float hi) { f32x2 v = {lo, hi}; bf16x2_t b = __builtin_convertvector(v, bf16x2_t); return __builtin_bit_cast(unsigned, b); }
; __device__ __forceinline__ void attn_wg_unit(const Args& args, int l, int u, LAS unsigned char* lds, int tid_in) {
;     ...
;     bf16_t* op = AMEM + (size_t)(row0 + r32) * MW + head * MHD;
; #pragma unroll
;     for (int dt = 0; dt < 8; ++dt)
; #pragma unroll
;         for (int ig = 0; ig < 4; ++ig) {
;             u32x2 w; w.x = cvtpk(ot[dt][4 * ig] * inv, ot[dt][4 * ig + 1] * inv); w.y = cvtpk(ot[dt][4 * ig + 2] * inv, ot[dt][4 * ig + 3] * inv);
;             *(u32x2*)(op + 32 * dt + 8 * ig + 4 * hh) = w;
;         }
; __global__ void __launch_bounds__(512, 2) mk_fwd(Args args) {
;     ...
;             for (int u = vcu; u < 256; u += G) attn_wg_unit(args, l, u, lds, tid);
	v_cvt_pk_bf16_f32 v2, v2, v3
	v_cvt_pk_bf16_f32 v3, v4, v5
	global_store_dwordx2 v[134:135], v[2:3], off offset:240
	v_pk_mul_f32 v[2:3], v[132:133], v[66:67] op_sel_hi:[0,1]
	v_pk_mul_f32 v[4:5], v[132:133], v[68:69] op_sel_hi:[0,1]
	v_cvt_pk_bf16_f32 v2, v2, v3
	v_cvt_pk_bf16_f32 v3, v4, v5
	global_store_dwordx2 v[134:135], v[2:3], off offset:256
	v_pk_mul_f32 v[2:3], v[132:133], v[70:71] op_sel_hi:[0,1]
	v_pk_mul_f32 v[4:5], v[132:133], v[72:73] op_sel_hi:[0,1]
	v_cvt_pk_bf16_f32 v2, v2, v3
	v_cvt_pk_bf16_f32 v3, v4, v5
	global_store_dwordx2 v[134:135], v[2:3], off offset:272
	v_pk_mul_f32 v[2:3], v[132:133], v[74:75] op_sel_hi:[0,1]
	v_pk_mul_f32 v[4:5], v[132:133], v[76:77] op_sel_hi:[0,1]
	v_cvt_pk_bf16_f32 v2, v2, v3
	v_cvt_pk_bf16_f32 v3, v4, v5
	global_store_dwordx2 v[134:135], v[2:3], off offset:288
	v_pk_mul_f32 v[2:3], v[132:133], v[78:79] op_sel_hi:[0,1]
	v_pk_mul_f32 v[4:5], v[132:133], v[80:81] op_sel_hi:[0,1]
	v_cvt_pk_bf16_f32 v2, v2, v3
	v_cvt_pk_bf16_f32 v3, v4, v5
	global_store_dwordx2 v[134:135], v[2:3], off offset:304
	v_pk_mul_f32 v[2:3], v[132:133], v[98:99] op_sel_hi:[0,1]
	v_pk_mul_f32 v[4:5], v[132:133], v[100:101] op_sel_hi:[0,1]
	v_cvt_pk_bf16_f32 v2, v2, v3
	v_cvt_pk_bf16_f32 v3, v4, v5
	global_store_dwordx2 v[134:135], v[2:3], off offset:320
	v_pk_mul_f32 v[2:3], v[132:133], v[102:103] op_sel_hi:[0,1]
	v_pk_mul_f32 v[4:5], v[132:133], v[104:105] op_sel_hi:[0,1]
	v_cvt_pk_bf16_f32 v2, v2, v3
	v_cvt_pk_bf16_f32 v3, v4, v5
	global_store_dwordx2 v[134:135], v[2:3], off offset:336
	v_pk_mul_f32 v[2:3], v[132:133], v[106:107] op_sel_hi:[0,1]
	v_pk_mul_f32 v[4:5], v[132:133], v[108:109] op_sel_hi:[0,1]
	v_cvt_pk_bf16_f32 v2, v2, v3
	v_cvt_pk_bf16_f32 v3, v4, v5
	global_store_dwordx2 v[134:135], v[2:3], off offset:352
	v_pk_mul_f32 v[2:3], v[132:133], v[110:111] op_sel_hi:[0,1]
	v_pk_mul_f32 v[4:5], v[132:133], v[112:113] op_sel_hi:[0,1]
	v_cvt_pk_bf16_f32 v2, v2, v3
	v_cvt_pk_bf16_f32 v3, v4, v5
	global_store_dwordx2 v[134:135], v[2:3], off offset:368
	v_pk_mul_f32 v[2:3], v[132:133], v[82:83] op_sel_hi:[0,1]
	v_pk_mul_f32 v[4:5], v[132:133], v[84:85] op_sel_hi:[0,1]
	v_cvt_pk_bf16_f32 v2, v2, v3
	v_cvt_pk_bf16_f32 v3, v4, v5
	global_store_dwordx2 v[134:135], v[2:3], off offset:384
	v_pk_mul_f32 v[2:3], v[132:133], v[86:87] op_sel_hi:[0,1]
	v_pk_mul_f32 v[4:5], v[132:133], v[88:89] op_sel_hi:[0,1]
	v_cvt_pk_bf16_f32 v2, v2, v3
	v_cvt_pk_bf16_f32 v3, v4, v5
	global_store_dwordx2 v[134:135], v[2:3], off offset:400
	v_pk_mul_f32 v[2:3], v[132:133], v[90:91] op_sel_hi:[0,1]
	v_pk_mul_f32 v[4:5], v[132:133], v[92:93] op_sel_hi:[0,1]
	v_cvt_pk_bf16_f32 v2, v2, v3
	v_cvt_pk_bf16_f32 v3, v4, v5
	global_store_dwordx2 v[134:135], v[2:3], off offset:416
	v_pk_mul_f32 v[2:3], v[132:133], v[94:95] op_sel_hi:[0,1]
	v_pk_mul_f32 v[4:5], v[132:133], v[96:97] op_sel_hi:[0,1]
	v_cvt_pk_bf16_f32 v2, v2, v3
	v_cvt_pk_bf16_f32 v3, v4, v5
	global_store_dwordx2 v[134:135], v[2:3], off offset:432
	v_pk_mul_f32 v[2:3], v[132:133], v[114:115] op_sel_hi:[0,1]
	v_pk_mul_f32 v[4:5], v[132:133], v[116:117] op_sel_hi:[0,1]
	v_cvt_pk_bf16_f32 v2, v2, v3
	v_cvt_pk_bf16_f32 v3, v4, v5
	global_store_dwordx2 v[134:135], v[2:3], off offset:448
	v_pk_mul_f32 v[2:3], v[132:133], v[118:119] op_sel_hi:[0,1]
	v_pk_mul_f32 v[4:5], v[132:133], v[120:121] op_sel_hi:[0,1]
	v_cvt_pk_bf16_f32 v2, v2, v3
	v_cvt_pk_bf16_f32 v3, v4, v5
	global_store_dwordx2 v[134:135], v[2:3], off offset:464
	v_pk_mul_f32 v[2:3], v[132:133], v[122:123] op_sel_hi:[0,1]
	v_pk_mul_f32 v[4:5], v[132:133], v[124:125] op_sel_hi:[0,1]
	v_cvt_pk_bf16_f32 v2, v2, v3
	v_cvt_pk_bf16_f32 v3, v4, v5
	global_store_dwordx2 v[134:135], v[2:3], off offset:480
	v_pk_mul_f32 v[2:3], v[132:133], v[126:127] op_sel_hi:[0,1]
	v_pk_mul_f32 v[4:5], v[132:133], v[128:129] op_sel_hi:[0,1]
	v_cvt_pk_bf16_f32 v2, v2, v3
	v_cvt_pk_bf16_f32 v3, v4, v5
	global_store_dwordx2 v[134:135], v[2:3], off offset:496
	s_cbranch_scc0 .LBB0_646
